# K-loop back edge: counter/pointer bumps and exit test moved in front of the last barrier of the iteration, only the branch stays behind it (6 GEMM loops)
# baseline (speedup 1.0000x reference)
; #define PG8_STAGE(bufoff, gbase, voff) do { _Pragma("unroll") for (int _i = 0; _i < 2; ++_i) \
;         __builtin_amdgcn_global_load_lds((const unsigned*)((const char*)(gbase) + (voff)[_i]), (PG8_LAS unsigned*)(lds + (bufoff) + ldsw + _i * 8192), 16, 0, 0); } while (0)
; #define PG8_LDA(dst, b, h) do { _Pragma("unroll") for (int m = 0; m < 4; ++m) _Pragma("unroll") for (int k = 0; k < 2; ++k) dst[m][k] = *(const PG8_LAS bf16x8*)(lds + PG8_SA(b, h) + aoff + m * 2048 + k * 1024); } while (0)
; #define PG8_LDB(dst, b, h) do { _Pragma("unroll") for (int n = 0; n < 2; ++n) _Pragma("unroll") for (int k = 0; k < 2; ++k) dst[n][k] = *(const PG8_LAS bf16x8*)(lds + PG8_SB(b, h) + boff + n * 2048 + k * 1024); } while (0)
; #define PG8_MMA(ai, bj, At, Bt) do { __builtin_amdgcn_s_setprio(1); _Pragma("unroll") for (int m = 0; m < 4; ++m) _Pragma("unroll") for (int n = 0; n < 2; ++n) _Pragma("unroll") for (int k = 0; k < 2; ++k) \
;         acc[ai][bj][m][n] = __builtin_amdgcn_mfma_f32_16x16x32_bf16(Bt[n][k], At[m][k], acc[ai][bj][m][n], 0, 0, 0); __builtin_amdgcn_s_setprio(0); } while (0)
; #define PG8_WAIT_V(n) asm volatile("s_waitcnt vmcnt(" #n ")" ::: "memory")
; #define PG8_WAIT_L(n) asm volatile("s_waitcnt lgkmcnt(" #n ")" ::: "memory")
; #define PG8_BAR __builtin_amdgcn_s_barrier()
; #define PG8_SCHED __builtin_amdgcn_sched_barrier(0)
; template <class Epi, class Sched, bool ALIGN_EPI = false, bool SP2 = false>
; __device__ __forceinline__ void gemm_phase(PG8_LAS unsigned char* lds, const Gemm g, const Sched& S, const Epi& E) {
;     ...
;             PG8_LDB(B0, 0, 0); PG8_LDB(B1, 0, 1); PG8_SCHED; PG8_LDA(At, 0, 0); PG8_STAGE(PG8_SA(1, 1), a1 + hstepA, voffA);
;             PG8_WAIT_V(8); PG8_WAIT_L(0); PG8_BAR; PG8_MMA(0, 0, At, B0); PG8_MMA(0, 1, At, B1); PG8_BAR; PG8_SCHED;
;             PG8_LDA(At, 0, 1); PG8_STAGE(PG8_SB(0, 0), b2, voffB); PG8_STAGE(PG8_SB(0, 1), b2 + hstepB, voffB); PG8_STAGE(PG8_SA(0, 0), a2, voffA);
;             PG8_WAIT_V(8); PG8_WAIT_L(0); PG8_BAR; PG8_MMA(1, 0, At, B0); PG8_MMA(1, 1, At, B1); PG8_BAR; PG8_SCHED;
.LBB0_171:
	v_add_u32_e32 v76, 0x10000, v162
	v_add_u32_e32 v158, 0x14000, v162
	ds_read_b128 v[64:67], v76
	ds_read_b128 v[68:71], v76 offset:1024
	ds_read_b128 v[72:75], v76 offset:2048
	ds_read_b128 v[76:79], v76 offset:3072
	ds_read_b128 v[154:157], v158
	ds_read_b128 v[164:167], v158 offset:1024
	ds_read_b128 v[168:171], v158 offset:2048
	ds_read_b128 v[172:175], v158 offset:3072
	ds_read_b128 v[176:179], v163
	ds_read_b128 v[180:183], v163 offset:1024
	ds_read_b128 v[184:187], v163 offset:2048
	ds_read_b128 v[194:197], v163 offset:3072
	ds_read_b128 v[230:233], v163 offset:4096
	ds_read_b128 v[234:237], v163 offset:5120
	ds_read_b128 v[238:241], v163 offset:6144
	ds_read_b128 v[242:245], v163 offset:7168
	s_add_u32 s50, s8, 0xfffc0080
	s_addc_u32 s51, s9, -1
	s_add_i32 s60, 0, 0x10000
	s_cmp_eq_u32 s59, 12
	s_cselect_b32 s53, s11, s51
	s_cselect_b32 s52, s37, s50
	s_cselect_b32 s51, s35, s58
	s_cselect_b32 s50, s54, s55
	s_add_i32 s62, 0, 0x14000
	s_add_i32 m0, s57, 0xc000
	v_lshl_add_u64 v[158:159], s[8:9], 0, v[150:151]
	global_load_lds_dwordx4 v[158:159], off
	s_add_i32 m0, s57, 0xe000
	v_lshl_add_u64 v[158:159], s[8:9], 0, v[152:153]
	global_load_lds_dwordx4 v[158:159], off
	s_waitcnt vmcnt(8)
	s_waitcnt lgkmcnt(0)
	s_barrier
	s_setprio 1
	s_waitcnt lgkmcnt(0)
	v_mfma_f32_16x16x32_bf16 v[140:143], v[64:67], v[176:179], v[140:143]
	v_mfma_f32_16x16x32_bf16 v[136:139], v[72:75], v[176:179], v[136:139]
	v_mfma_f32_16x16x32_bf16 v[124:127], v[64:67], v[184:187], v[124:127]
	v_mfma_f32_16x16x32_bf16 v[120:123], v[72:75], v[184:187], v[120:123]
	v_mfma_f32_16x16x32_bf16 v[108:111], v[64:67], v[230:233], v[108:111]
	v_mfma_f32_16x16x32_bf16 v[104:107], v[72:75], v[230:233], v[104:107]
	v_mfma_f32_16x16x32_bf16 v[92:95], v[64:67], v[238:241], v[92:95]
	v_mfma_f32_16x16x32_bf16 v[88:91], v[72:75], v[238:241], v[88:91]
	v_mfma_f32_16x16x32_bf16 v[140:143], v[68:71], v[180:183], v[140:143]
	v_mfma_f32_16x16x32_bf16 v[136:139], v[76:79], v[180:183], v[136:139]
	v_mfma_f32_16x16x32_bf16 v[124:127], v[68:71], v[194:197], v[124:127]
	v_mfma_f32_16x16x32_bf16 v[120:123], v[76:79], v[194:197], v[120:123]
	v_mfma_f32_16x16x32_bf16 v[108:111], v[68:71], v[234:237], v[108:111]
	v_mfma_f32_16x16x32_bf16 v[104:107], v[76:79], v[234:237], v[104:107]
	v_mfma_f32_16x16x32_bf16 v[92:95], v[68:71], v[242:245], v[92:95]
	v_mfma_f32_16x16x32_bf16 v[88:91], v[76:79], v[242:245], v[88:91]
	s_setprio 0
	s_setprio 1
	v_mfma_f32_16x16x32_bf16 v[132:135], v[154:157], v[176:179], v[132:135]
	v_mfma_f32_16x16x32_bf16 v[128:131], v[168:171], v[176:179], v[128:131]
	v_mfma_f32_16x16x32_bf16 v[116:119], v[154:157], v[184:187], v[116:119]
	v_mfma_f32_16x16x32_bf16 v[112:115], v[168:171], v[184:187], v[112:115]
	v_mfma_f32_16x16x32_bf16 v[100:103], v[154:157], v[230:233], v[100:103]
	v_mfma_f32_16x16x32_bf16 v[96:99], v[168:171], v[230:233], v[96:99]
	v_mfma_f32_16x16x32_bf16 v[84:87], v[154:157], v[238:241], v[84:87]
	v_mfma_f32_16x16x32_bf16 v[80:83], v[168:171], v[238:241], v[80:83]
	v_mfma_f32_16x16x32_bf16 v[132:135], v[164:167], v[180:183], v[132:135]
	v_mfma_f32_16x16x32_bf16 v[128:131], v[172:175], v[180:183], v[128:131]
	v_mfma_f32_16x16x32_bf16 v[116:119], v[164:167], v[194:197], v[116:119]
	v_mfma_f32_16x16x32_bf16 v[112:115], v[172:175], v[194:197], v[112:115]
	v_mfma_f32_16x16x32_bf16 v[100:103], v[164:167], v[234:237], v[100:103]
	v_mfma_f32_16x16x32_bf16 v[96:99], v[172:175], v[234:237], v[96:99]
	v_mfma_f32_16x16x32_bf16 v[84:87], v[164:167], v[242:245], v[84:87]
	v_mfma_f32_16x16x32_bf16 v[80:83], v[172:175], v[242:245], v[80:83]
	s_setprio 0
	s_barrier
	ds_read_b128 v[176:179], v163 offset:16384
	ds_read_b128 v[180:183], v163 offset:17408
	ds_read_b128 v[184:187], v163 offset:18432
	ds_read_b128 v[194:197], v163 offset:19456
	ds_read_b128 v[230:233], v163 offset:20480
	ds_read_b128 v[234:237], v163 offset:21504
	ds_read_b128 v[238:241], v163 offset:22528
	ds_read_b128 v[242:245], v163 offset:23552
	s_add_i32 s60, s60, s69
	s_mov_b32 m0, s60
	v_lshl_add_u64 v[158:159], s[50:51], 0, v[188:189]
	global_load_lds_dwordx4 v[158:159], off
	s_add_i32 m0, s60, 0x2000
	s_add_u32 s60, s50, 0x40000
	v_lshl_add_u64 v[246:247], s[50:51], 0, v[148:149]
	s_addc_u32 s61, s51, 0
	s_add_i32 s62, s62, s69
	global_load_lds_dwordx4 v[246:247], off
	v_lshl_add_u64 v[248:249], s[60:61], 0, v[188:189]
	s_mov_b32 m0, s62
	v_lshl_add_u64 v[250:251], s[52:53], 0, v[146:147]
	global_load_lds_dwordx4 v[248:249], off
	s_add_i32 m0, s62, 0x2000
	v_lshl_add_u64 v[248:249], s[60:61], 0, v[148:149]
	global_load_lds_dwordx4 v[248:249], off
	s_mov_b32 m0, s57
	v_lshl_add_u64 v[248:249], s[52:53], 0, v[144:145]
	global_load_lds_dwordx4 v[248:249], off
	s_mov_b32 m0, s78
	s_nop 0
	global_load_lds_dwordx4 v[250:251], off
	s_waitcnt vmcnt(8)
	s_waitcnt lgkmcnt(0)
	s_barrier
; #define PG8_STAGE(bufoff, gbase, voff) do { _Pragma("unroll") for (int _i = 0; _i < 2; ++_i) \
;         __builtin_amdgcn_global_load_lds((const unsigned*)((const char*)(gbase) + (voff)[_i]), (PG8_LAS unsigned*)(lds + (bufoff) + ldsw + _i * 8192), 16, 0, 0); } while (0)
; #define PG8_LDA(dst, b, h) do { _Pragma("unroll") for (int m = 0; m < 4; ++m) _Pragma("unroll") for (int k = 0; k < 2; ++k) dst[m][k] = *(const PG8_LAS bf16x8*)(lds + PG8_SA(b, h) + aoff + m * 2048 + k * 1024); } while (0)
; #define PG8_LDB(dst, b, h) do { _Pragma("unroll") for (int n = 0; n < 2; ++n) _Pragma("unroll") for (int k = 0; k < 2; ++k) dst[n][k] = *(const PG8_LAS bf16x8*)(lds + PG8_SB(b, h) + boff + n * 2048 + k * 1024); } while (0)
; #define PG8_MMA(ai, bj, At, Bt) do { __builtin_amdgcn_s_setprio(1); _Pragma("unroll") for (int m = 0; m < 4; ++m) _Pragma("unroll") for (int n = 0; n < 2; ++n) _Pragma("unroll") for (int k = 0; k < 2; ++k) \
;         acc[ai][bj][m][n] = __builtin_amdgcn_mfma_f32_16x16x32_bf16(Bt[n][k], At[m][k], acc[ai][bj][m][n], 0, 0, 0); __builtin_amdgcn_s_setprio(0); } while (0)
; #define PG8_WAIT_V(n) asm volatile("s_waitcnt vmcnt(" #n ")" ::: "memory")
; #define PG8_WAIT_L(n) asm volatile("s_waitcnt lgkmcnt(" #n ")" ::: "memory")
; #define PG8_BAR __builtin_amdgcn_s_barrier()
; #define PG8_SCHED __builtin_amdgcn_sched_barrier(0)
; template <class Epi, class Sched, bool ALIGN_EPI = false, bool SP2 = false>
; __device__ __forceinline__ void gemm_phase(PG8_LAS unsigned char* lds, const Gemm g, const Sched& S, const Epi& E) {
;     ...
;             PG8_WAIT_V(8); PG8_WAIT_L(0); PG8_BAR; PG8_MMA(1, 0, At, B0); PG8_MMA(1, 1, At, B1); PG8_BAR; PG8_SCHED;
;             PG8_LDB(B0, 1, 0); PG8_LDB(B1, 1, 1); PG8_SCHED; PG8_LDA(At, 1, 0); PG8_STAGE(PG8_SA(0, 1), a2 + hstepA, voffA);
;             PG8_WAIT_V(8); PG8_WAIT_L(0); PG8_BAR; PG8_MMA(0, 0, At, B0); PG8_MMA(0, 1, At, B1); PG8_BAR; PG8_SCHED;
	s_setprio 1
	s_waitcnt lgkmcnt(0)
	v_mfma_f32_16x16x32_bf16 v[60:63], v[64:67], v[176:179], v[60:63]
	v_mfma_f32_16x16x32_bf16 v[56:59], v[72:75], v[176:179], v[56:59]
	v_mfma_f32_16x16x32_bf16 v[44:47], v[64:67], v[184:187], v[44:47]
	v_mfma_f32_16x16x32_bf16 v[40:43], v[72:75], v[184:187], v[40:43]
	v_mfma_f32_16x16x32_bf16 v[28:31], v[64:67], v[230:233], v[28:31]
	v_mfma_f32_16x16x32_bf16 v[24:27], v[72:75], v[230:233], v[24:27]
	v_mfma_f32_16x16x32_bf16 v[12:15], v[64:67], v[238:241], v[12:15]
	v_mfma_f32_16x16x32_bf16 v[8:11], v[72:75], v[238:241], v[8:11]
	v_mfma_f32_16x16x32_bf16 v[60:63], v[68:71], v[180:183], v[60:63]
	v_mfma_f32_16x16x32_bf16 v[56:59], v[76:79], v[180:183], v[56:59]
	v_mfma_f32_16x16x32_bf16 v[44:47], v[68:71], v[194:197], v[44:47]
	v_mfma_f32_16x16x32_bf16 v[40:43], v[76:79], v[194:197], v[40:43]
	v_mfma_f32_16x16x32_bf16 v[28:31], v[68:71], v[234:237], v[28:31]
	v_mfma_f32_16x16x32_bf16 v[24:27], v[76:79], v[234:237], v[24:27]
	v_mfma_f32_16x16x32_bf16 v[12:15], v[68:71], v[242:245], v[12:15]
	v_mfma_f32_16x16x32_bf16 v[8:11], v[76:79], v[242:245], v[8:11]
	s_setprio 0
	s_setprio 1
	v_mfma_f32_16x16x32_bf16 v[52:55], v[154:157], v[176:179], v[52:55]
	v_mfma_f32_16x16x32_bf16 v[48:51], v[168:171], v[176:179], v[48:51]
	v_mfma_f32_16x16x32_bf16 v[36:39], v[154:157], v[184:187], v[36:39]
	v_mfma_f32_16x16x32_bf16 v[32:35], v[168:171], v[184:187], v[32:35]
	v_mfma_f32_16x16x32_bf16 v[20:23], v[154:157], v[230:233], v[20:23]
	v_mfma_f32_16x16x32_bf16 v[16:19], v[168:171], v[230:233], v[16:19]
	v_mfma_f32_16x16x32_bf16 v[4:7], v[154:157], v[238:241], v[4:7]
	v_mfma_f32_16x16x32_bf16 v[0:3], v[168:171], v[238:241], v[0:3]
	v_mfma_f32_16x16x32_bf16 v[52:55], v[164:167], v[180:183], v[52:55]
	v_mfma_f32_16x16x32_bf16 v[48:51], v[172:175], v[180:183], v[48:51]
	v_mfma_f32_16x16x32_bf16 v[36:39], v[164:167], v[194:197], v[36:39]
	v_mfma_f32_16x16x32_bf16 v[32:35], v[172:175], v[194:197], v[32:35]
	v_mfma_f32_16x16x32_bf16 v[20:23], v[164:167], v[234:237], v[20:23]
	v_mfma_f32_16x16x32_bf16 v[16:19], v[172:175], v[234:237], v[16:19]
	v_mfma_f32_16x16x32_bf16 v[4:7], v[164:167], v[242:245], v[4:7]
	v_mfma_f32_16x16x32_bf16 v[0:3], v[172:175], v[242:245], v[0:3]
	s_setprio 0
	s_barrier
	v_add_u32_e32 v76, 0x18000, v162
	v_add_u32_e32 v172, 0x1c000, v162
	ds_read_b128 v[64:67], v76
	ds_read_b128 v[68:71], v76 offset:1024
	ds_read_b128 v[72:75], v76 offset:2048
	ds_read_b128 v[76:79], v76 offset:3072
	ds_read_b128 v[154:157], v172
	ds_read_b128 v[164:167], v172 offset:1024
	ds_read_b128 v[168:171], v172 offset:2048
	ds_read_b128 v[172:175], v172 offset:3072
	ds_read_b128 v[176:179], v163 offset:32768
	ds_read_b128 v[180:183], v163 offset:33792
	ds_read_b128 v[184:187], v163 offset:34816
	ds_read_b128 v[194:197], v163 offset:35840
	ds_read_b128 v[230:233], v163 offset:36864
	ds_read_b128 v[234:237], v163 offset:37888
	ds_read_b128 v[238:241], v163 offset:38912
	ds_read_b128 v[242:245], v163 offset:39936
	s_add_i32 s60, 0, 0x18000
	s_add_i32 s61, 0, 0x1c000
	s_add_u32 s52, s52, 0x40000
	s_addc_u32 s53, s53, 0
	s_mov_b32 m0, s81
	v_lshl_add_u64 v[252:253], s[52:53], 0, v[144:145]
	global_load_lds_dwordx4 v[252:253], off
	s_mov_b32 m0, s80
	v_lshl_add_u64 v[252:253], s[52:53], 0, v[146:147]
	global_load_lds_dwordx4 v[252:253], off
	s_waitcnt vmcnt(8)
	s_waitcnt lgkmcnt(0)
	s_barrier
	s_setprio 1
	s_waitcnt lgkmcnt(0)
	v_mfma_f32_16x16x32_bf16 v[140:143], v[64:67], v[176:179], v[140:143]
	v_mfma_f32_16x16x32_bf16 v[136:139], v[72:75], v[176:179], v[136:139]
	v_mfma_f32_16x16x32_bf16 v[124:127], v[64:67], v[184:187], v[124:127]
	v_mfma_f32_16x16x32_bf16 v[120:123], v[72:75], v[184:187], v[120:123]
	v_mfma_f32_16x16x32_bf16 v[108:111], v[64:67], v[230:233], v[108:111]
	v_mfma_f32_16x16x32_bf16 v[104:107], v[72:75], v[230:233], v[104:107]
	v_mfma_f32_16x16x32_bf16 v[92:95], v[64:67], v[238:241], v[92:95]
	v_mfma_f32_16x16x32_bf16 v[88:91], v[72:75], v[238:241], v[88:91]
	v_mfma_f32_16x16x32_bf16 v[140:143], v[68:71], v[180:183], v[140:143]
	v_mfma_f32_16x16x32_bf16 v[136:139], v[76:79], v[180:183], v[136:139]
	v_mfma_f32_16x16x32_bf16 v[124:127], v[68:71], v[194:197], v[124:127]
	v_mfma_f32_16x16x32_bf16 v[120:123], v[76:79], v[194:197], v[120:123]
	v_mfma_f32_16x16x32_bf16 v[108:111], v[68:71], v[234:237], v[108:111]
	v_mfma_f32_16x16x32_bf16 v[104:107], v[76:79], v[234:237], v[104:107]
	v_mfma_f32_16x16x32_bf16 v[92:95], v[68:71], v[242:245], v[92:95]
	v_mfma_f32_16x16x32_bf16 v[88:91], v[76:79], v[242:245], v[88:91]
	s_setprio 0
	s_setprio 1
	v_mfma_f32_16x16x32_bf16 v[132:135], v[154:157], v[176:179], v[132:135]
	v_mfma_f32_16x16x32_bf16 v[128:131], v[168:171], v[176:179], v[128:131]
	v_mfma_f32_16x16x32_bf16 v[116:119], v[154:157], v[184:187], v[116:119]
	v_mfma_f32_16x16x32_bf16 v[112:115], v[168:171], v[184:187], v[112:115]
	v_mfma_f32_16x16x32_bf16 v[100:103], v[154:157], v[230:233], v[100:103]
	v_mfma_f32_16x16x32_bf16 v[96:99], v[168:171], v[230:233], v[96:99]
	v_mfma_f32_16x16x32_bf16 v[84:87], v[154:157], v[238:241], v[84:87]
	v_mfma_f32_16x16x32_bf16 v[80:83], v[168:171], v[238:241], v[80:83]
	v_mfma_f32_16x16x32_bf16 v[132:135], v[164:167], v[180:183], v[132:135]
	v_mfma_f32_16x16x32_bf16 v[128:131], v[172:175], v[180:183], v[128:131]
	v_mfma_f32_16x16x32_bf16 v[116:119], v[164:167], v[194:197], v[116:119]
	v_mfma_f32_16x16x32_bf16 v[112:115], v[172:175], v[194:197], v[112:115]
	v_mfma_f32_16x16x32_bf16 v[100:103], v[164:167], v[234:237], v[100:103]
	v_mfma_f32_16x16x32_bf16 v[96:99], v[172:175], v[234:237], v[96:99]
	v_mfma_f32_16x16x32_bf16 v[84:87], v[164:167], v[242:245], v[84:87]
	v_mfma_f32_16x16x32_bf16 v[80:83], v[172:175], v[242:245], v[80:83]
	s_setprio 0
	s_barrier
; #define PG8_STAGE(bufoff, gbase, voff) do { _Pragma("unroll") for (int _i = 0; _i < 2; ++_i) \
;         __builtin_amdgcn_global_load_lds((const unsigned*)((const char*)(gbase) + (voff)[_i]), (PG8_LAS unsigned*)(lds + (bufoff) + ldsw + _i * 8192), 16, 0, 0); } while (0)
; #define PG8_LDA(dst, b, h) do { _Pragma("unroll") for (int m = 0; m < 4; ++m) _Pragma("unroll") for (int k = 0; k < 2; ++k) dst[m][k] = *(const PG8_LAS bf16x8*)(lds + PG8_SA(b, h) + aoff + m * 2048 + k * 1024); } while (0)
; #define PG8_WAIT_V(n) asm volatile("s_waitcnt vmcnt(" #n ")" ::: "memory")
; template <class Epi, class Sched, bool ALIGN_EPI = false, bool SP2 = false>
; __device__ __forceinline__ void gemm_phase(PG8_LAS unsigned char* lds, const Gemm g, const Sched& S, const Epi& E) {
;     ...
;             PG8_LDA(At, 1, 1); PG8_STAGE(PG8_SB(1, 0), b3, voffB); PG8_STAGE(PG8_SB(1, 1), b3 + hstepB, voffB); PG8_STAGE(PG8_SA(1, 0), a3, voffA);
;             PG8_WAIT_V(8); PG8_WAIT_L(0); PG8_BAR; PG8_MMA(1, 0, At, B0); PG8_MMA(1, 1, At, B1); PG8_BAR; PG8_SCHED;
;             } else {
;             PG8_LDB(B0, 0, 0); PG8_SCHED; PG8_LDA(At, 0, 0); PG8_STAGE(PG8_SA(1, 1), a1 + hstepA, voffA);
;             PG8_WAIT_L(8); PG8_BAR; PG8_WAIT_L(0); PG8_MMA(0, 0, At, B0); PG8_BAR; PG8_SCHED;
;             PG8_LDB(B1, 0, 1); PG8_STAGE(PG8_SB(0, 0), b2, voffB);
;             PG8_BAR; PG8_WAIT_L(0); PG8_MMA(0, 1, At, B1); PG8_BAR;
;             PG8_LDA(At, 0, 1); PG8_STAGE(PG8_SA(0, 0), a2, voffA);
;             PG8_BAR; PG8_WAIT_L(0); PG8_MMA(1, 0, At, B0); PG8_BAR; PG8_SCHED;
;             PG8_STAGE(PG8_SB(0, 1), b2 + hstepB, voffB);
;             PG8_WAIT_V(6); PG8_BAR; PG8_MMA(1, 1, At, B1); PG8_BAR;
;             PG8_LDB(B0, 1, 0); PG8_SCHED; PG8_LDA(At, 1, 0); PG8_STAGE(PG8_SA(0, 1), a2 + hstepA, voffA);
;             PG8_WAIT_L(8); PG8_BAR; PG8_WAIT_L(0); PG8_MMA(0, 0, At, B0); PG8_BAR; PG8_SCHED;
;             PG8_LDB(B1, 1, 1); PG8_STAGE(PG8_SB(1, 0), b3, voffB);
;             PG8_BAR; PG8_WAIT_L(0); PG8_MMA(0, 1, At, B1); PG8_BAR;
;             PG8_LDA(At, 1, 1); PG8_STAGE(PG8_SA(1, 0), a3, voffA);
;             PG8_BAR; PG8_WAIT_L(0); PG8_MMA(1, 0, At, B0); PG8_BAR; PG8_SCHED;
;             PG8_STAGE(PG8_SB(1, 1), b3 + hstepB, voffB);
;             PG8_WAIT_V(6); PG8_BAR; PG8_MMA(1, 1, At, B1); PG8_BAR;
;             }
;         }
;         if constexpr (ALIGN_EPI) { if (wr == 0) PG8_BAR; }
	ds_read_b128 v[176:179], v163 offset:49152
	ds_read_b128 v[180:183], v163 offset:50176
	ds_read_b128 v[184:187], v163 offset:51200
	ds_read_b128 v[194:197], v163 offset:52224
	ds_read_b128 v[230:233], v163 offset:53248
	ds_read_b128 v[234:237], v163 offset:54272
	ds_read_b128 v[238:241], v163 offset:55296
	ds_read_b128 v[242:245], v163 offset:56320
	s_add_i32 s52, s60, s69
	s_mov_b32 m0, s52
	v_lshl_add_u64 v[158:159], v[158:159], 0, s[94:95]
	global_load_lds_dwordx4 v[158:159], off
	s_add_i32 m0, s52, 0x2000
	s_add_u32 s50, s50, 0x40080
	v_lshl_add_u64 v[158:159], v[246:247], 0, s[94:95]
	s_addc_u32 s51, s51, 0
	s_add_i32 s52, s61, s69
	global_load_lds_dwordx4 v[158:159], off
	s_mov_b32 m0, s52
	v_lshl_add_u64 v[158:159], s[50:51], 0, v[188:189]
	global_load_lds_dwordx4 v[158:159], off
	s_add_i32 m0, s52, 0x2000
	v_lshl_add_u64 v[158:159], s[50:51], 0, v[148:149]
	global_load_lds_dwordx4 v[158:159], off
	s_mov_b32 m0, s2
	v_lshl_add_u64 v[158:159], v[248:249], 0, s[94:95]
	global_load_lds_dwordx4 v[158:159], off
	s_mov_b32 m0, s4
	v_lshl_add_u64 v[158:159], v[250:251], 0, s[94:95]
	global_load_lds_dwordx4 v[158:159], off
	s_waitcnt vmcnt(8)
	s_waitcnt lgkmcnt(0)
	s_barrier
	s_setprio 1
	s_waitcnt lgkmcnt(0)
	v_mfma_f32_16x16x32_bf16 v[60:63], v[64:67], v[176:179], v[60:63]
	v_mfma_f32_16x16x32_bf16 v[56:59], v[72:75], v[176:179], v[56:59]
	v_mfma_f32_16x16x32_bf16 v[44:47], v[64:67], v[184:187], v[44:47]
	v_mfma_f32_16x16x32_bf16 v[40:43], v[72:75], v[184:187], v[40:43]
	v_mfma_f32_16x16x32_bf16 v[28:31], v[64:67], v[230:233], v[28:31]
	v_mfma_f32_16x16x32_bf16 v[24:27], v[72:75], v[230:233], v[24:27]
	v_mfma_f32_16x16x32_bf16 v[12:15], v[64:67], v[238:241], v[12:15]
	v_mfma_f32_16x16x32_bf16 v[8:11], v[72:75], v[238:241], v[8:11]
	v_mfma_f32_16x16x32_bf16 v[60:63], v[68:71], v[180:183], v[60:63]
	v_mfma_f32_16x16x32_bf16 v[56:59], v[76:79], v[180:183], v[56:59]
	v_mfma_f32_16x16x32_bf16 v[44:47], v[68:71], v[194:197], v[44:47]
	v_mfma_f32_16x16x32_bf16 v[40:43], v[76:79], v[194:197], v[40:43]
	v_mfma_f32_16x16x32_bf16 v[28:31], v[68:71], v[234:237], v[28:31]
	v_mfma_f32_16x16x32_bf16 v[24:27], v[76:79], v[234:237], v[24:27]
	v_mfma_f32_16x16x32_bf16 v[12:15], v[68:71], v[242:245], v[12:15]
	v_mfma_f32_16x16x32_bf16 v[8:11], v[76:79], v[242:245], v[8:11]
	s_setprio 0
	s_setprio 1
	v_mfma_f32_16x16x32_bf16 v[52:55], v[154:157], v[176:179], v[52:55]
	v_mfma_f32_16x16x32_bf16 v[48:51], v[168:171], v[176:179], v[48:51]
	v_mfma_f32_16x16x32_bf16 v[36:39], v[154:157], v[184:187], v[36:39]
	v_mfma_f32_16x16x32_bf16 v[32:35], v[168:171], v[184:187], v[32:35]
	v_mfma_f32_16x16x32_bf16 v[20:23], v[154:157], v[230:233], v[20:23]
	v_mfma_f32_16x16x32_bf16 v[16:19], v[168:171], v[230:233], v[16:19]
	v_mfma_f32_16x16x32_bf16 v[4:7], v[154:157], v[238:241], v[4:7]
	v_mfma_f32_16x16x32_bf16 v[0:3], v[168:171], v[238:241], v[0:3]
	v_mfma_f32_16x16x32_bf16 v[52:55], v[164:167], v[180:183], v[52:55]
	v_mfma_f32_16x16x32_bf16 v[48:51], v[172:175], v[180:183], v[48:51]
	v_mfma_f32_16x16x32_bf16 v[36:39], v[164:167], v[194:197], v[36:39]
	v_mfma_f32_16x16x32_bf16 v[32:35], v[172:175], v[194:197], v[32:35]
	v_mfma_f32_16x16x32_bf16 v[20:23], v[164:167], v[234:237], v[20:23]
	v_mfma_f32_16x16x32_bf16 v[16:19], v[172:175], v[234:237], v[16:19]
	v_mfma_f32_16x16x32_bf16 v[4:7], v[164:167], v[242:245], v[4:7]
	v_mfma_f32_16x16x32_bf16 v[0:3], v[172:175], v[242:245], v[0:3]
	s_setprio 0
	s_add_i32 s59, s59, 2
	s_add_u32 s8, s8, 0x100
	s_addc_u32 s9, s9, 0
	s_add_u32 s55, s55, 0x100
	s_addc_u32 s58, s58, 0
	s_cmp_gt_u32 s59, 13
	s_barrier
	s_cbranch_scc0 .LBB0_171
	s_and_b64 vcc, exec, s[30:31]
	s_cbranch_vccz .LBB0_174
	s_barrier

; #define PG8_STAGE(bufoff, gbase, voff) do { _Pragma("unroll") for (int _i = 0; _i < 2; ++_i) \
;         __builtin_amdgcn_global_load_lds((const unsigned*)((const char*)(gbase) + (voff)[_i]), (PG8_LAS unsigned*)(lds + (bufoff) + ldsw + _i * 8192), 16, 0, 0); } while (0)
; #define PG8_LDA(dst, b, h) do { _Pragma("unroll") for (int m = 0; m < 4; ++m) _Pragma("unroll") for (int k = 0; k < 2; ++k) dst[m][k] = *(const PG8_LAS bf16x8*)(lds + PG8_SA(b, h) + aoff + m * 2048 + k * 1024); } while (0)
; #define PG8_LDB(dst, b, h) do { _Pragma("unroll") for (int n = 0; n < 2; ++n) _Pragma("unroll") for (int k = 0; k < 2; ++k) dst[n][k] = *(const PG8_LAS bf16x8*)(lds + PG8_SB(b, h) + boff + n * 2048 + k * 1024); } while (0)
; #define PG8_MMA(ai, bj, At, Bt) do { __builtin_amdgcn_s_setprio(1); _Pragma("unroll") for (int m = 0; m < 4; ++m) _Pragma("unroll") for (int n = 0; n < 2; ++n) _Pragma("unroll") for (int k = 0; k < 2; ++k) \
;         acc[ai][bj][m][n] = __builtin_amdgcn_mfma_f32_16x16x32_bf16(Bt[n][k], At[m][k], acc[ai][bj][m][n], 0, 0, 0); __builtin_amdgcn_s_setprio(0); } while (0)
; #define PG8_WAIT_V(n) asm volatile("s_waitcnt vmcnt(" #n ")" ::: "memory")
; #define PG8_WAIT_L(n) asm volatile("s_waitcnt lgkmcnt(" #n ")" ::: "memory")
; #define PG8_BAR __builtin_amdgcn_s_barrier()
; #define PG8_SCHED __builtin_amdgcn_sched_barrier(0)
; template <class Epi, class Sched, bool ALIGN_EPI = false, bool SP2 = false>
; __device__ __forceinline__ void gemm_phase(PG8_LAS unsigned char* lds, const Gemm g, const Sched& S, const Epi& E) {
;     ...
;             PG8_LDB(B0, 0, 0); PG8_LDB(B1, 0, 1); PG8_SCHED; PG8_LDA(At, 0, 0); PG8_STAGE(PG8_SA(1, 1), a1 + hstepA, voffA);
;             PG8_WAIT_V(8); PG8_WAIT_L(0); PG8_BAR; PG8_MMA(0, 0, At, B0); PG8_MMA(0, 1, At, B1); PG8_BAR; PG8_SCHED;
;             PG8_LDA(At, 0, 1); PG8_STAGE(PG8_SB(0, 0), b2, voffB); PG8_STAGE(PG8_SB(0, 1), b2 + hstepB, voffB); PG8_STAGE(PG8_SA(0, 0), a2, voffA);
;             PG8_WAIT_V(8); PG8_WAIT_L(0); PG8_BAR; PG8_MMA(1, 0, At, B0); PG8_MMA(1, 1, At, B1); PG8_BAR; PG8_SCHED;
.LBB0_712:
	v_add_u32_e32 v154, 0x10000, v144
	v_add_u32_e32 v170, 0x14000, v144
	ds_read_b128 v[138:141], v154
	ds_read_b128 v[146:149], v154 offset:1024
	ds_read_b128 v[150:153], v154 offset:2048
	ds_read_b128 v[154:157], v154 offset:3072
	ds_read_b128 v[158:161], v170
	ds_read_b128 v[162:165], v170 offset:1024
	ds_read_b128 v[166:169], v170 offset:2048
	ds_read_b128 v[170:173], v170 offset:3072
	ds_read_b128 v[174:177], v145
	ds_read_b128 v[178:181], v145 offset:1024
	ds_read_b128 v[182:185], v145 offset:2048
	ds_read_b128 v[192:195], v145 offset:3072
	ds_read_b128 v[230:233], v145 offset:4096
	ds_read_b128 v[234:237], v145 offset:5120
	ds_read_b128 v[238:241], v145 offset:6144
	ds_read_b128 v[242:245], v145 offset:7168
	s_add_u32 s28, s26, 0xfffc0080
	s_addc_u32 s29, s27, -1
	s_add_i32 s33, 0, 0x10000
	s_cmp_eq_u32 s19, 12
	s_cselect_b32 s31, s1, s29
	s_cselect_b32 s30, s2, s28
	s_cselect_b32 s29, s3, s17
	s_cselect_b32 s28, s4, s9
	s_add_i32 s51, 0, 0x14000
	s_add_i32 m0, s25, 0xc000
	v_lshl_add_u64 v[186:187], s[26:27], 0, v[134:135]
	global_load_lds_dwordx4 v[186:187], off
	s_add_i32 m0, s25, 0xe000
	v_lshl_add_u64 v[186:187], s[26:27], 0, v[136:137]
	global_load_lds_dwordx4 v[186:187], off
	s_waitcnt vmcnt(8)
	s_waitcnt lgkmcnt(0)
	s_barrier
	s_setprio 1
	s_waitcnt lgkmcnt(0)
	v_mfma_f32_16x16x32_bf16 v[124:127], v[138:141], v[174:177], v[124:127]
	v_mfma_f32_16x16x32_bf16 v[120:123], v[150:153], v[174:177], v[120:123]
	v_mfma_f32_16x16x32_bf16 v[108:111], v[138:141], v[182:185], v[108:111]
	v_mfma_f32_16x16x32_bf16 v[104:107], v[150:153], v[182:185], v[104:107]
	v_mfma_f32_16x16x32_bf16 v[92:95], v[138:141], v[230:233], v[92:95]
	v_mfma_f32_16x16x32_bf16 v[88:91], v[150:153], v[230:233], v[88:91]
	v_mfma_f32_16x16x32_bf16 v[76:79], v[138:141], v[238:241], v[76:79]
	v_mfma_f32_16x16x32_bf16 v[72:75], v[150:153], v[238:241], v[72:75]
	v_mfma_f32_16x16x32_bf16 v[124:127], v[146:149], v[178:181], v[124:127]
	v_mfma_f32_16x16x32_bf16 v[120:123], v[154:157], v[178:181], v[120:123]
	v_mfma_f32_16x16x32_bf16 v[108:111], v[146:149], v[192:195], v[108:111]
	v_mfma_f32_16x16x32_bf16 v[104:107], v[154:157], v[192:195], v[104:107]
	v_mfma_f32_16x16x32_bf16 v[92:95], v[146:149], v[234:237], v[92:95]
	v_mfma_f32_16x16x32_bf16 v[88:91], v[154:157], v[234:237], v[88:91]
	v_mfma_f32_16x16x32_bf16 v[76:79], v[146:149], v[242:245], v[76:79]
	v_mfma_f32_16x16x32_bf16 v[72:75], v[154:157], v[242:245], v[72:75]
	s_setprio 0
	s_setprio 1
	v_mfma_f32_16x16x32_bf16 v[116:119], v[158:161], v[174:177], v[116:119]
	v_mfma_f32_16x16x32_bf16 v[112:115], v[166:169], v[174:177], v[112:115]
	v_mfma_f32_16x16x32_bf16 v[100:103], v[158:161], v[182:185], v[100:103]
	v_mfma_f32_16x16x32_bf16 v[96:99], v[166:169], v[182:185], v[96:99]
	v_mfma_f32_16x16x32_bf16 v[84:87], v[158:161], v[230:233], v[84:87]
	v_mfma_f32_16x16x32_bf16 v[80:83], v[166:169], v[230:233], v[80:83]
	v_mfma_f32_16x16x32_bf16 v[68:71], v[158:161], v[238:241], v[68:71]
	v_mfma_f32_16x16x32_bf16 v[64:67], v[166:169], v[238:241], v[64:67]
	v_mfma_f32_16x16x32_bf16 v[116:119], v[162:165], v[178:181], v[116:119]
	v_mfma_f32_16x16x32_bf16 v[112:115], v[170:173], v[178:181], v[112:115]
	v_mfma_f32_16x16x32_bf16 v[100:103], v[162:165], v[192:195], v[100:103]
	v_mfma_f32_16x16x32_bf16 v[96:99], v[170:173], v[192:195], v[96:99]
	v_mfma_f32_16x16x32_bf16 v[84:87], v[162:165], v[234:237], v[84:87]
	v_mfma_f32_16x16x32_bf16 v[80:83], v[170:173], v[234:237], v[80:83]
	v_mfma_f32_16x16x32_bf16 v[68:71], v[162:165], v[242:245], v[68:71]
	v_mfma_f32_16x16x32_bf16 v[64:67], v[170:173], v[242:245], v[64:67]
	s_setprio 0
	s_barrier
	ds_read_b128 v[174:177], v145 offset:16384
	ds_read_b128 v[178:181], v145 offset:17408
	ds_read_b128 v[182:185], v145 offset:18432
	ds_read_b128 v[192:195], v145 offset:19456
	ds_read_b128 v[230:233], v145 offset:20480
	ds_read_b128 v[234:237], v145 offset:21504
	ds_read_b128 v[238:241], v145 offset:22528
	ds_read_b128 v[242:245], v145 offset:23552
	s_add_i32 s33, s33, s39
	s_mov_b32 m0, s33
	v_lshl_add_u64 v[186:187], s[28:29], 0, v[188:189]
	global_load_lds_dwordx4 v[186:187], off
	s_add_i32 m0, s33, 0x2000
	s_add_u32 s52, s28, 0x40000
	v_lshl_add_u64 v[196:197], s[28:29], 0, v[132:133]
	s_addc_u32 s53, s29, 0
	s_add_i32 s33, s51, s39
	global_load_lds_dwordx4 v[196:197], off
	v_lshl_add_u64 v[246:247], s[52:53], 0, v[188:189]
	s_mov_b32 m0, s33
	v_lshl_add_u64 v[248:249], s[30:31], 0, v[130:131]
	global_load_lds_dwordx4 v[246:247], off
	s_add_i32 m0, s33, 0x2000
	v_lshl_add_u64 v[246:247], s[52:53], 0, v[132:133]
	global_load_lds_dwordx4 v[246:247], off
	s_mov_b32 m0, s25
	v_lshl_add_u64 v[246:247], s[30:31], 0, v[128:129]
	global_load_lds_dwordx4 v[246:247], off
	s_mov_b32 m0, s40
	s_nop 0
	global_load_lds_dwordx4 v[248:249], off
	s_waitcnt vmcnt(8)
	s_waitcnt lgkmcnt(0)
	s_barrier
; #define PG8_STAGE(bufoff, gbase, voff) do { _Pragma("unroll") for (int _i = 0; _i < 2; ++_i) \
;         __builtin_amdgcn_global_load_lds((const unsigned*)((const char*)(gbase) + (voff)[_i]), (PG8_LAS unsigned*)(lds + (bufoff) + ldsw + _i * 8192), 16, 0, 0); } while (0)
; #define PG8_LDA(dst, b, h) do { _Pragma("unroll") for (int m = 0; m < 4; ++m) _Pragma("unroll") for (int k = 0; k < 2; ++k) dst[m][k] = *(const PG8_LAS bf16x8*)(lds + PG8_SA(b, h) + aoff + m * 2048 + k * 1024); } while (0)
; #define PG8_LDB(dst, b, h) do { _Pragma("unroll") for (int n = 0; n < 2; ++n) _Pragma("unroll") for (int k = 0; k < 2; ++k) dst[n][k] = *(const PG8_LAS bf16x8*)(lds + PG8_SB(b, h) + boff + n * 2048 + k * 1024); } while (0)
; #define PG8_MMA(ai, bj, At, Bt) do { __builtin_amdgcn_s_setprio(1); _Pragma("unroll") for (int m = 0; m < 4; ++m) _Pragma("unroll") for (int n = 0; n < 2; ++n) _Pragma("unroll") for (int k = 0; k < 2; ++k) \
;         acc[ai][bj][m][n] = __builtin_amdgcn_mfma_f32_16x16x32_bf16(Bt[n][k], At[m][k], acc[ai][bj][m][n], 0, 0, 0); __builtin_amdgcn_s_setprio(0); } while (0)
; #define PG8_WAIT_V(n) asm volatile("s_waitcnt vmcnt(" #n ")" ::: "memory")
; #define PG8_WAIT_L(n) asm volatile("s_waitcnt lgkmcnt(" #n ")" ::: "memory")
; #define PG8_BAR __builtin_amdgcn_s_barrier()
; #define PG8_SCHED __builtin_amdgcn_sched_barrier(0)
; template <class Epi, class Sched, bool ALIGN_EPI = false, bool SP2 = false>
; __device__ __forceinline__ void gemm_phase(PG8_LAS unsigned char* lds, const Gemm g, const Sched& S, const Epi& E) {
;     ...
;             PG8_WAIT_V(8); PG8_WAIT_L(0); PG8_BAR; PG8_MMA(1, 0, At, B0); PG8_MMA(1, 1, At, B1); PG8_BAR; PG8_SCHED;
;             PG8_LDB(B0, 1, 0); PG8_LDB(B1, 1, 1); PG8_SCHED; PG8_LDA(At, 1, 0); PG8_STAGE(PG8_SA(0, 1), a2 + hstepA, voffA);
;             PG8_WAIT_V(8); PG8_WAIT_L(0); PG8_BAR; PG8_MMA(0, 0, At, B0); PG8_MMA(0, 1, At, B1); PG8_BAR; PG8_SCHED;
	s_setprio 1
	s_waitcnt lgkmcnt(0)
	v_mfma_f32_16x16x32_bf16 v[60:63], v[138:141], v[174:177], v[60:63]
	v_mfma_f32_16x16x32_bf16 v[56:59], v[150:153], v[174:177], v[56:59]
	v_mfma_f32_16x16x32_bf16 v[44:47], v[138:141], v[182:185], v[44:47]
	v_mfma_f32_16x16x32_bf16 v[40:43], v[150:153], v[182:185], v[40:43]
	v_mfma_f32_16x16x32_bf16 v[28:31], v[138:141], v[230:233], v[28:31]
	v_mfma_f32_16x16x32_bf16 v[24:27], v[150:153], v[230:233], v[24:27]
	v_mfma_f32_16x16x32_bf16 v[12:15], v[138:141], v[238:241], v[12:15]
	v_mfma_f32_16x16x32_bf16 v[8:11], v[150:153], v[238:241], v[8:11]
	v_mfma_f32_16x16x32_bf16 v[60:63], v[146:149], v[178:181], v[60:63]
	v_mfma_f32_16x16x32_bf16 v[56:59], v[154:157], v[178:181], v[56:59]
	v_mfma_f32_16x16x32_bf16 v[44:47], v[146:149], v[192:195], v[44:47]
	v_mfma_f32_16x16x32_bf16 v[40:43], v[154:157], v[192:195], v[40:43]
	v_mfma_f32_16x16x32_bf16 v[28:31], v[146:149], v[234:237], v[28:31]
	v_mfma_f32_16x16x32_bf16 v[24:27], v[154:157], v[234:237], v[24:27]
	v_mfma_f32_16x16x32_bf16 v[12:15], v[146:149], v[242:245], v[12:15]
	v_mfma_f32_16x16x32_bf16 v[8:11], v[154:157], v[242:245], v[8:11]
	s_setprio 0
	s_setprio 1
	v_mfma_f32_16x16x32_bf16 v[52:55], v[158:161], v[174:177], v[52:55]
	v_mfma_f32_16x16x32_bf16 v[48:51], v[166:169], v[174:177], v[48:51]
	v_mfma_f32_16x16x32_bf16 v[36:39], v[158:161], v[182:185], v[36:39]
	v_mfma_f32_16x16x32_bf16 v[32:35], v[166:169], v[182:185], v[32:35]
	v_mfma_f32_16x16x32_bf16 v[20:23], v[158:161], v[230:233], v[20:23]
	v_mfma_f32_16x16x32_bf16 v[16:19], v[166:169], v[230:233], v[16:19]
	v_mfma_f32_16x16x32_bf16 v[4:7], v[158:161], v[238:241], v[4:7]
	v_mfma_f32_16x16x32_bf16 v[0:3], v[166:169], v[238:241], v[0:3]
	v_mfma_f32_16x16x32_bf16 v[52:55], v[162:165], v[178:181], v[52:55]
	v_mfma_f32_16x16x32_bf16 v[48:51], v[170:173], v[178:181], v[48:51]
	v_mfma_f32_16x16x32_bf16 v[36:39], v[162:165], v[192:195], v[36:39]
	v_mfma_f32_16x16x32_bf16 v[32:35], v[170:173], v[192:195], v[32:35]
	v_mfma_f32_16x16x32_bf16 v[20:23], v[162:165], v[234:237], v[20:23]
	v_mfma_f32_16x16x32_bf16 v[16:19], v[170:173], v[234:237], v[16:19]
	v_mfma_f32_16x16x32_bf16 v[4:7], v[162:165], v[242:245], v[4:7]
	v_mfma_f32_16x16x32_bf16 v[0:3], v[170:173], v[242:245], v[0:3]
	s_setprio 0
	s_barrier
	v_add_u32_e32 v154, 0x18000, v144
	v_add_u32_e32 v170, 0x1c000, v144
	ds_read_b128 v[138:141], v154
	ds_read_b128 v[146:149], v154 offset:1024
	ds_read_b128 v[150:153], v154 offset:2048
	ds_read_b128 v[154:157], v154 offset:3072
	ds_read_b128 v[158:161], v170
	ds_read_b128 v[162:165], v170 offset:1024
	ds_read_b128 v[166:169], v170 offset:2048
	ds_read_b128 v[170:173], v170 offset:3072
	ds_read_b128 v[174:177], v145 offset:32768
	ds_read_b128 v[178:181], v145 offset:33792
	ds_read_b128 v[182:185], v145 offset:34816
	ds_read_b128 v[192:195], v145 offset:35840
	ds_read_b128 v[230:233], v145 offset:36864
	ds_read_b128 v[234:237], v145 offset:37888
	ds_read_b128 v[238:241], v145 offset:38912
	ds_read_b128 v[242:245], v145 offset:39936
	s_add_i32 s33, 0, 0x18000
	s_add_i32 s51, 0, 0x1c000
	s_add_u32 s30, s30, 0x40000
	s_addc_u32 s31, s31, 0
	s_mov_b32 m0, s41
	v_lshl_add_u64 v[250:251], s[30:31], 0, v[128:129]
	global_load_lds_dwordx4 v[250:251], off
	s_mov_b32 m0, s42
	v_lshl_add_u64 v[250:251], s[30:31], 0, v[130:131]
	global_load_lds_dwordx4 v[250:251], off
	s_waitcnt vmcnt(8)
	s_waitcnt lgkmcnt(0)
	s_barrier
	s_setprio 1
	s_waitcnt lgkmcnt(0)
	v_mfma_f32_16x16x32_bf16 v[124:127], v[138:141], v[174:177], v[124:127]
	v_mfma_f32_16x16x32_bf16 v[120:123], v[150:153], v[174:177], v[120:123]
	v_mfma_f32_16x16x32_bf16 v[108:111], v[138:141], v[182:185], v[108:111]
	v_mfma_f32_16x16x32_bf16 v[104:107], v[150:153], v[182:185], v[104:107]
	v_mfma_f32_16x16x32_bf16 v[92:95], v[138:141], v[230:233], v[92:95]
	v_mfma_f32_16x16x32_bf16 v[88:91], v[150:153], v[230:233], v[88:91]
	v_mfma_f32_16x16x32_bf16 v[76:79], v[138:141], v[238:241], v[76:79]
	v_mfma_f32_16x16x32_bf16 v[72:75], v[150:153], v[238:241], v[72:75]
	v_mfma_f32_16x16x32_bf16 v[124:127], v[146:149], v[178:181], v[124:127]
	v_mfma_f32_16x16x32_bf16 v[120:123], v[154:157], v[178:181], v[120:123]
	v_mfma_f32_16x16x32_bf16 v[108:111], v[146:149], v[192:195], v[108:111]
	v_mfma_f32_16x16x32_bf16 v[104:107], v[154:157], v[192:195], v[104:107]
	v_mfma_f32_16x16x32_bf16 v[92:95], v[146:149], v[234:237], v[92:95]
	v_mfma_f32_16x16x32_bf16 v[88:91], v[154:157], v[234:237], v[88:91]
	v_mfma_f32_16x16x32_bf16 v[76:79], v[146:149], v[242:245], v[76:79]
	v_mfma_f32_16x16x32_bf16 v[72:75], v[154:157], v[242:245], v[72:75]
	s_setprio 0
	s_setprio 1
	v_mfma_f32_16x16x32_bf16 v[116:119], v[158:161], v[174:177], v[116:119]
	v_mfma_f32_16x16x32_bf16 v[112:115], v[166:169], v[174:177], v[112:115]
	v_mfma_f32_16x16x32_bf16 v[100:103], v[158:161], v[182:185], v[100:103]
	v_mfma_f32_16x16x32_bf16 v[96:99], v[166:169], v[182:185], v[96:99]
	v_mfma_f32_16x16x32_bf16 v[84:87], v[158:161], v[230:233], v[84:87]
	v_mfma_f32_16x16x32_bf16 v[80:83], v[166:169], v[230:233], v[80:83]
	v_mfma_f32_16x16x32_bf16 v[68:71], v[158:161], v[238:241], v[68:71]
	v_mfma_f32_16x16x32_bf16 v[64:67], v[166:169], v[238:241], v[64:67]
	v_mfma_f32_16x16x32_bf16 v[116:119], v[162:165], v[178:181], v[116:119]
	v_mfma_f32_16x16x32_bf16 v[112:115], v[170:173], v[178:181], v[112:115]
	v_mfma_f32_16x16x32_bf16 v[100:103], v[162:165], v[192:195], v[100:103]
	v_mfma_f32_16x16x32_bf16 v[96:99], v[170:173], v[192:195], v[96:99]
	v_mfma_f32_16x16x32_bf16 v[84:87], v[162:165], v[234:237], v[84:87]
	v_mfma_f32_16x16x32_bf16 v[80:83], v[170:173], v[234:237], v[80:83]
	v_mfma_f32_16x16x32_bf16 v[68:71], v[162:165], v[242:245], v[68:71]
	v_mfma_f32_16x16x32_bf16 v[64:67], v[170:173], v[242:245], v[64:67]
	s_setprio 0
	s_barrier
; #define PG8_STAGE(bufoff, gbase, voff) do { _Pragma("unroll") for (int _i = 0; _i < 2; ++_i) \
;         __builtin_amdgcn_global_load_lds((const unsigned*)((const char*)(gbase) + (voff)[_i]), (PG8_LAS unsigned*)(lds + (bufoff) + ldsw + _i * 8192), 16, 0, 0); } while (0)
; #define PG8_LDA(dst, b, h) do { _Pragma("unroll") for (int m = 0; m < 4; ++m) _Pragma("unroll") for (int k = 0; k < 2; ++k) dst[m][k] = *(const PG8_LAS bf16x8*)(lds + PG8_SA(b, h) + aoff + m * 2048 + k * 1024); } while (0)
; #define PG8_WAIT_V(n) asm volatile("s_waitcnt vmcnt(" #n ")" ::: "memory")
; template <class Epi, class Sched, bool ALIGN_EPI = false, bool SP2 = false>
; __device__ __forceinline__ void gemm_phase(PG8_LAS unsigned char* lds, const Gemm g, const Sched& S, const Epi& E) {
;     ...
;             PG8_LDA(At, 1, 1); PG8_STAGE(PG8_SB(1, 0), b3, voffB); PG8_STAGE(PG8_SB(1, 1), b3 + hstepB, voffB); PG8_STAGE(PG8_SA(1, 0), a3, voffA);
;             PG8_WAIT_V(8); PG8_WAIT_L(0); PG8_BAR; PG8_MMA(1, 0, At, B0); PG8_MMA(1, 1, At, B1); PG8_BAR; PG8_SCHED;
;             } else {
;             PG8_LDB(B0, 0, 0); PG8_SCHED; PG8_LDA(At, 0, 0); PG8_STAGE(PG8_SA(1, 1), a1 + hstepA, voffA);
;             PG8_WAIT_L(8); PG8_BAR; PG8_WAIT_L(0); PG8_MMA(0, 0, At, B0); PG8_BAR; PG8_SCHED;
;             PG8_LDB(B1, 0, 1); PG8_STAGE(PG8_SB(0, 0), b2, voffB);
;             PG8_BAR; PG8_WAIT_L(0); PG8_MMA(0, 1, At, B1); PG8_BAR;
;             PG8_LDA(At, 0, 1); PG8_STAGE(PG8_SA(0, 0), a2, voffA);
;             PG8_BAR; PG8_WAIT_L(0); PG8_MMA(1, 0, At, B0); PG8_BAR; PG8_SCHED;
;             PG8_STAGE(PG8_SB(0, 1), b2 + hstepB, voffB);
;             PG8_WAIT_V(6); PG8_BAR; PG8_MMA(1, 1, At, B1); PG8_BAR;
;             PG8_LDB(B0, 1, 0); PG8_SCHED; PG8_LDA(At, 1, 0); PG8_STAGE(PG8_SA(0, 1), a2 + hstepA, voffA);
;             PG8_WAIT_L(8); PG8_BAR; PG8_WAIT_L(0); PG8_MMA(0, 0, At, B0); PG8_BAR; PG8_SCHED;
;             PG8_LDB(B1, 1, 1); PG8_STAGE(PG8_SB(1, 0), b3, voffB);
;             PG8_BAR; PG8_WAIT_L(0); PG8_MMA(0, 1, At, B1); PG8_BAR;
;             PG8_LDA(At, 1, 1); PG8_STAGE(PG8_SA(1, 0), a3, voffA);
;             PG8_BAR; PG8_WAIT_L(0); PG8_MMA(1, 0, At, B0); PG8_BAR; PG8_SCHED;
;             PG8_STAGE(PG8_SB(1, 1), b3 + hstepB, voffB);
;             PG8_WAIT_V(6); PG8_BAR; PG8_MMA(1, 1, At, B1); PG8_BAR;
;             }
;         }
;         if constexpr (ALIGN_EPI) { if (wr == 0) PG8_BAR; }
	ds_read_b128 v[174:177], v145 offset:49152
	ds_read_b128 v[178:181], v145 offset:50176
	ds_read_b128 v[182:185], v145 offset:51200
	ds_read_b128 v[192:195], v145 offset:52224
	ds_read_b128 v[230:233], v145 offset:53248
	ds_read_b128 v[234:237], v145 offset:54272
	ds_read_b128 v[238:241], v145 offset:55296
	ds_read_b128 v[242:245], v145 offset:56320
	s_add_i32 s30, s33, s39
	s_mov_b32 m0, s30
	v_lshl_add_u64 v[186:187], v[186:187], 0, s[94:95]
	global_load_lds_dwordx4 v[186:187], off
	s_add_i32 m0, s30, 0x2000
	s_add_u32 s28, s28, 0x40080
	v_lshl_add_u64 v[186:187], v[196:197], 0, s[94:95]
	s_addc_u32 s29, s29, 0
	s_add_i32 s30, s51, s39
	global_load_lds_dwordx4 v[186:187], off
	s_mov_b32 m0, s30
	v_lshl_add_u64 v[186:187], s[28:29], 0, v[188:189]
	global_load_lds_dwordx4 v[186:187], off
	s_add_i32 m0, s30, 0x2000
	v_lshl_add_u64 v[186:187], s[28:29], 0, v[132:133]
	global_load_lds_dwordx4 v[186:187], off
	s_mov_b32 m0, s47
	v_lshl_add_u64 v[186:187], v[246:247], 0, s[94:95]
	global_load_lds_dwordx4 v[186:187], off
	s_mov_b32 m0, s48
	v_lshl_add_u64 v[186:187], v[248:249], 0, s[94:95]
	global_load_lds_dwordx4 v[186:187], off
	s_waitcnt vmcnt(8)
	s_waitcnt lgkmcnt(0)
	s_barrier
	s_setprio 1
	s_waitcnt lgkmcnt(0)
	v_mfma_f32_16x16x32_bf16 v[60:63], v[138:141], v[174:177], v[60:63]
	v_mfma_f32_16x16x32_bf16 v[56:59], v[150:153], v[174:177], v[56:59]
	v_mfma_f32_16x16x32_bf16 v[44:47], v[138:141], v[182:185], v[44:47]
	v_mfma_f32_16x16x32_bf16 v[40:43], v[150:153], v[182:185], v[40:43]
	v_mfma_f32_16x16x32_bf16 v[28:31], v[138:141], v[230:233], v[28:31]
	v_mfma_f32_16x16x32_bf16 v[24:27], v[150:153], v[230:233], v[24:27]
	v_mfma_f32_16x16x32_bf16 v[12:15], v[138:141], v[238:241], v[12:15]
	v_mfma_f32_16x16x32_bf16 v[8:11], v[150:153], v[238:241], v[8:11]
	v_mfma_f32_16x16x32_bf16 v[60:63], v[146:149], v[178:181], v[60:63]
	v_mfma_f32_16x16x32_bf16 v[56:59], v[154:157], v[178:181], v[56:59]
	v_mfma_f32_16x16x32_bf16 v[44:47], v[146:149], v[192:195], v[44:47]
	v_mfma_f32_16x16x32_bf16 v[40:43], v[154:157], v[192:195], v[40:43]
	v_mfma_f32_16x16x32_bf16 v[28:31], v[146:149], v[234:237], v[28:31]
	v_mfma_f32_16x16x32_bf16 v[24:27], v[154:157], v[234:237], v[24:27]
	v_mfma_f32_16x16x32_bf16 v[12:15], v[146:149], v[242:245], v[12:15]
	v_mfma_f32_16x16x32_bf16 v[8:11], v[154:157], v[242:245], v[8:11]
	s_setprio 0
	s_setprio 1
	v_mfma_f32_16x16x32_bf16 v[52:55], v[158:161], v[174:177], v[52:55]
	v_mfma_f32_16x16x32_bf16 v[48:51], v[166:169], v[174:177], v[48:51]
	v_mfma_f32_16x16x32_bf16 v[36:39], v[158:161], v[182:185], v[36:39]
	v_mfma_f32_16x16x32_bf16 v[32:35], v[166:169], v[182:185], v[32:35]
	v_mfma_f32_16x16x32_bf16 v[20:23], v[158:161], v[230:233], v[20:23]
	v_mfma_f32_16x16x32_bf16 v[16:19], v[166:169], v[230:233], v[16:19]
	v_mfma_f32_16x16x32_bf16 v[4:7], v[158:161], v[238:241], v[4:7]
	v_mfma_f32_16x16x32_bf16 v[0:3], v[166:169], v[238:241], v[0:3]
	v_mfma_f32_16x16x32_bf16 v[52:55], v[162:165], v[178:181], v[52:55]
	v_mfma_f32_16x16x32_bf16 v[48:51], v[170:173], v[178:181], v[48:51]
	v_mfma_f32_16x16x32_bf16 v[36:39], v[162:165], v[192:195], v[36:39]
	v_mfma_f32_16x16x32_bf16 v[32:35], v[170:173], v[192:195], v[32:35]
	v_mfma_f32_16x16x32_bf16 v[20:23], v[162:165], v[234:237], v[20:23]
	v_mfma_f32_16x16x32_bf16 v[16:19], v[170:173], v[234:237], v[16:19]
	v_mfma_f32_16x16x32_bf16 v[4:7], v[162:165], v[242:245], v[4:7]
	v_mfma_f32_16x16x32_bf16 v[0:3], v[170:173], v[242:245], v[0:3]
	s_setprio 0
	s_add_i32 s19, s19, 2
	s_add_u32 s26, s26, 0x100
	s_addc_u32 s27, s27, 0
	s_add_u32 s9, s9, 0x100
	s_addc_u32 s17, s17, 0
	s_cmp_gt_u32 s19, 13
	s_barrier
	s_cbranch_scc0 .LBB0_712
	s_and_b64 vcc, exec, s[14:15]
	s_cbranch_vccz .LBB0_715
	s_barrier

; #define PG8_STAGE(bufoff, gbase, voff) do { _Pragma("unroll") for (int _i = 0; _i < 2; ++_i) \
;         __builtin_amdgcn_global_load_lds((const unsigned*)((const char*)(gbase) + (voff)[_i]), (PG8_LAS unsigned*)(lds + (bufoff) + ldsw + _i * 8192), 16, 0, 0); } while (0)
; #define PG8_LDA(dst, b, h) do { _Pragma("unroll") for (int m = 0; m < 4; ++m) _Pragma("unroll") for (int k = 0; k < 2; ++k) dst[m][k] = *(const PG8_LAS bf16x8*)(lds + PG8_SA(b, h) + aoff + m * 2048 + k * 1024); } while (0)
; #define PG8_LDB(dst, b, h) do { _Pragma("unroll") for (int n = 0; n < 2; ++n) _Pragma("unroll") for (int k = 0; k < 2; ++k) dst[n][k] = *(const PG8_LAS bf16x8*)(lds + PG8_SB(b, h) + boff + n * 2048 + k * 1024); } while (0)
; #define PG8_MMA(ai, bj, At, Bt) do { __builtin_amdgcn_s_setprio(1); _Pragma("unroll") for (int m = 0; m < 4; ++m) _Pragma("unroll") for (int n = 0; n < 2; ++n) _Pragma("unroll") for (int k = 0; k < 2; ++k) \
;         acc[ai][bj][m][n] = __builtin_amdgcn_mfma_f32_16x16x32_bf16(Bt[n][k], At[m][k], acc[ai][bj][m][n], 0, 0, 0); __builtin_amdgcn_s_setprio(0); } while (0)
; template <class Epi, class Sched, bool ALIGN_EPI = false, bool SP2 = false>
; __device__ __forceinline__ void gemm_phase(PG8_LAS unsigned char* lds, const Gemm g, const Sched& S, const Epi& E) {
;     ...
;         const char* nA = has_next ? (const char*)g.A + (size_t)nxt.pm * tstepA + (size_t)((nxt.pn / g.kdiv) * g.kmul) * 2 : cA; const char* nB = has_next ? (const char*)g.Bt + (size_t)nxt.pn * tstepB : cB;
; #pragma nounroll
;         for (int t = 0; t < nt; t += 2) {
;             const bool last = (t == nt - 2);
;             const char* a1 = cA + (size_t)(t + 1) * kstep;
;             const char* a2 = last ? nA : cA + (size_t)(t + 2) * kstep; const char* b2 = last ? nB : cB + (size_t)(t + 2) * kstep;
;             const char* a3 = a2 + kstep; const char* b3 = b2 + kstep;
;     ...
;             PG8_LDB(B0, 0, 0); PG8_LDB(B1, 0, 1); PG8_SCHED; PG8_LDA(At, 0, 0); PG8_STAGE(PG8_SA(1, 1), a1 + hstepA, voffA);
;             PG8_WAIT_V(8); PG8_WAIT_L(0); PG8_BAR; PG8_MMA(0, 0, At, B0); PG8_MMA(0, 1, At, B1); PG8_BAR; PG8_SCHED;
;             PG8_LDA(At, 0, 1); PG8_STAGE(PG8_SB(0, 0), b2, voffB); PG8_STAGE(PG8_SB(0, 1), b2 + hstepB, voffB); PG8_STAGE(PG8_SA(0, 0), a2, voffA);
;             PG8_WAIT_V(8); PG8_WAIT_L(0); PG8_BAR; PG8_MMA(1, 0, At, B0); PG8_MMA(1, 1, At, B1); PG8_BAR; PG8_SCHED;
.LBB0_901:
	v_add_u32_e32 v150, 0x10000, v136
	v_add_u32_e32 v166, 0x14000, v136
	ds_read_b128 v[138:141], v150
	ds_read_b128 v[142:145], v150 offset:1024
	ds_read_b128 v[146:149], v150 offset:2048
	ds_read_b128 v[150:153], v150 offset:3072
	ds_read_b128 v[154:157], v166
	ds_read_b128 v[158:161], v166 offset:1024
	ds_read_b128 v[162:165], v166 offset:2048
	ds_read_b128 v[166:169], v166 offset:3072
	ds_read_b128 v[170:173], v137
	ds_read_b128 v[174:177], v137 offset:1024
	ds_read_b128 v[178:181], v137 offset:2048
	ds_read_b128 v[182:185], v137 offset:3072
	ds_read_b128 v[192:195], v137 offset:4096
	ds_read_b128 v[230:233], v137 offset:5120
	ds_read_b128 v[234:237], v137 offset:6144
	ds_read_b128 v[238:241], v137 offset:7168
	s_add_u32 s44, s34, s38
	s_addc_u32 s45, s35, s39
	s_add_u32 s42, s44, 0x100
	s_addc_u32 s43, s45, 0
	s_and_b64 s[40:41], s[36:37], exec
	s_cselect_b32 s41, s27, s43
	s_cselect_b32 s40, s26, s42
	s_add_u32 s38, s30, s38
	s_addc_u32 s39, s31, s39
	s_add_u32 s38, s38, 0x100
	s_addc_u32 s39, s39, 0
	s_add_i32 s72, 0, 0x10000
	s_and_b64 s[36:37], s[36:37], exec
	s_cselect_b32 s43, s25, s39
	s_cselect_b32 s42, s63, s38
	s_add_i32 s37, 0, 0x14000
	s_add_u32 s46, s44, 0x50080
	s_addc_u32 s47, s45, 0
	s_add_i32 s71, s72, s49
	s_add_i32 m0, s51, 0xc000
	s_add_i32 s74, s51, 0xe000
	s_add_i32 s68, s71, 0x2000
	s_add_u32 s44, s42, 0x10000
	s_addc_u32 s45, s43, 0
	s_add_i32 s70, s37, s49
	s_add_i32 s69, s70, 0x2000
	s_add_i32 s67, 0, 0x18000
	s_add_i32 s66, 0, 0x1c000
	s_add_u32 s38, s40, 0x50000
	s_addc_u32 s39, s41, 0
	s_add_i32 s65, s67, s49
	s_add_i32 s64, s65, 0x2000
	s_add_u32 s36, s42, 0x10080
	s_addc_u32 s37, s43, 0
	s_add_i32 s73, s66, s49
	s_add_i32 s72, s73, 0x2000
	v_lshl_add_u64 v[186:187], s[46:47], 0, v[132:133]
	global_load_lds_dwordx4 v[186:187], off
	s_mov_b32 m0, s74
	v_lshl_add_u64 v[186:187], s[46:47], 0, v[130:131]
	global_load_lds_dwordx4 v[186:187], off
	s_waitcnt vmcnt(8)
	s_waitcnt lgkmcnt(0)
	s_barrier
	s_setprio 1
	s_waitcnt lgkmcnt(0)
	v_mfma_f32_16x16x32_bf16 v[124:127], v[138:141], v[170:173], v[124:127]
	v_mfma_f32_16x16x32_bf16 v[120:123], v[146:149], v[170:173], v[120:123]
	v_mfma_f32_16x16x32_bf16 v[116:119], v[138:141], v[178:181], v[116:119]
	v_mfma_f32_16x16x32_bf16 v[112:115], v[146:149], v[178:181], v[112:115]
	v_mfma_f32_16x16x32_bf16 v[100:103], v[138:141], v[192:195], v[100:103]
	v_mfma_f32_16x16x32_bf16 v[96:99], v[146:149], v[192:195], v[96:99]
	v_mfma_f32_16x16x32_bf16 v[84:87], v[138:141], v[234:237], v[84:87]
	v_mfma_f32_16x16x32_bf16 v[80:83], v[146:149], v[234:237], v[80:83]
	v_mfma_f32_16x16x32_bf16 v[124:127], v[142:145], v[174:177], v[124:127]
	v_mfma_f32_16x16x32_bf16 v[120:123], v[150:153], v[174:177], v[120:123]
	v_mfma_f32_16x16x32_bf16 v[116:119], v[142:145], v[182:185], v[116:119]
	v_mfma_f32_16x16x32_bf16 v[112:115], v[150:153], v[182:185], v[112:115]
	v_mfma_f32_16x16x32_bf16 v[100:103], v[142:145], v[230:233], v[100:103]
	v_mfma_f32_16x16x32_bf16 v[96:99], v[150:153], v[230:233], v[96:99]
	v_mfma_f32_16x16x32_bf16 v[84:87], v[142:145], v[238:241], v[84:87]
	v_mfma_f32_16x16x32_bf16 v[80:83], v[150:153], v[238:241], v[80:83]
	s_setprio 0
	s_setprio 1
	v_mfma_f32_16x16x32_bf16 v[108:111], v[154:157], v[170:173], v[108:111]
	v_mfma_f32_16x16x32_bf16 v[104:107], v[162:165], v[170:173], v[104:107]
	v_mfma_f32_16x16x32_bf16 v[92:95], v[154:157], v[178:181], v[92:95]
	v_mfma_f32_16x16x32_bf16 v[88:91], v[162:165], v[178:181], v[88:91]
	v_mfma_f32_16x16x32_bf16 v[76:79], v[154:157], v[192:195], v[76:79]
	v_mfma_f32_16x16x32_bf16 v[72:75], v[162:165], v[192:195], v[72:75]
	v_mfma_f32_16x16x32_bf16 v[68:71], v[154:157], v[234:237], v[68:71]
	v_mfma_f32_16x16x32_bf16 v[64:67], v[162:165], v[234:237], v[64:67]
	v_mfma_f32_16x16x32_bf16 v[108:111], v[158:161], v[174:177], v[108:111]
	v_mfma_f32_16x16x32_bf16 v[104:107], v[166:169], v[174:177], v[104:107]
	v_mfma_f32_16x16x32_bf16 v[92:95], v[158:161], v[182:185], v[92:95]
	v_mfma_f32_16x16x32_bf16 v[88:91], v[166:169], v[182:185], v[88:91]
	v_mfma_f32_16x16x32_bf16 v[76:79], v[158:161], v[230:233], v[76:79]
	v_mfma_f32_16x16x32_bf16 v[72:75], v[166:169], v[230:233], v[72:75]
	v_mfma_f32_16x16x32_bf16 v[68:71], v[158:161], v[238:241], v[68:71]
	v_mfma_f32_16x16x32_bf16 v[64:67], v[166:169], v[238:241], v[64:67]
	s_setprio 0
	s_barrier
	ds_read_b128 v[170:173], v137 offset:16384
	ds_read_b128 v[174:177], v137 offset:17408
	ds_read_b128 v[178:181], v137 offset:18432
	ds_read_b128 v[182:185], v137 offset:19456
	ds_read_b128 v[192:195], v137 offset:20480
	ds_read_b128 v[230:233], v137 offset:21504
	ds_read_b128 v[234:237], v137 offset:22528
	ds_read_b128 v[238:241], v137 offset:23552
	s_mov_b32 m0, s71
	v_lshl_add_u64 v[186:187], s[42:43], 0, v[188:189]
	global_load_lds_dwordx4 v[186:187], off
	v_lshl_add_u64 v[196:197], s[42:43], 0, v[128:129]
	s_mov_b32 m0, s68
	v_lshl_add_u64 v[242:243], s[44:45], 0, v[188:189]
	global_load_lds_dwordx4 v[196:197], off
	s_mov_b32 m0, s70
	v_lshl_add_u64 v[244:245], s[40:41], 0, v[130:131]
	global_load_lds_dwordx4 v[242:243], off
	s_mov_b32 m0, s69
	v_lshl_add_u64 v[242:243], s[44:45], 0, v[128:129]
	global_load_lds_dwordx4 v[242:243], off
	s_mov_b32 m0, s51
	v_lshl_add_u64 v[242:243], s[40:41], 0, v[132:133]
	global_load_lds_dwordx4 v[242:243], off
	s_mov_b32 m0, s52
	s_nop 0
	global_load_lds_dwordx4 v[244:245], off
	s_waitcnt vmcnt(8)
	s_waitcnt lgkmcnt(0)
	s_barrier
; #define PG8_STAGE(bufoff, gbase, voff) do { _Pragma("unroll") for (int _i = 0; _i < 2; ++_i) \
;         __builtin_amdgcn_global_load_lds((const unsigned*)((const char*)(gbase) + (voff)[_i]), (PG8_LAS unsigned*)(lds + (bufoff) + ldsw + _i * 8192), 16, 0, 0); } while (0)
; #define PG8_LDA(dst, b, h) do { _Pragma("unroll") for (int m = 0; m < 4; ++m) _Pragma("unroll") for (int k = 0; k < 2; ++k) dst[m][k] = *(const PG8_LAS bf16x8*)(lds + PG8_SA(b, h) + aoff + m * 2048 + k * 1024); } while (0)
; #define PG8_LDB(dst, b, h) do { _Pragma("unroll") for (int n = 0; n < 2; ++n) _Pragma("unroll") for (int k = 0; k < 2; ++k) dst[n][k] = *(const PG8_LAS bf16x8*)(lds + PG8_SB(b, h) + boff + n * 2048 + k * 1024); } while (0)
; #define PG8_MMA(ai, bj, At, Bt) do { __builtin_amdgcn_s_setprio(1); _Pragma("unroll") for (int m = 0; m < 4; ++m) _Pragma("unroll") for (int n = 0; n < 2; ++n) _Pragma("unroll") for (int k = 0; k < 2; ++k) \
;         acc[ai][bj][m][n] = __builtin_amdgcn_mfma_f32_16x16x32_bf16(Bt[n][k], At[m][k], acc[ai][bj][m][n], 0, 0, 0); __builtin_amdgcn_s_setprio(0); } while (0)
; #define PG8_WAIT_V(n) asm volatile("s_waitcnt vmcnt(" #n ")" ::: "memory")
; #define PG8_WAIT_L(n) asm volatile("s_waitcnt lgkmcnt(" #n ")" ::: "memory")
; #define PG8_BAR __builtin_amdgcn_s_barrier()
; #define PG8_SCHED __builtin_amdgcn_sched_barrier(0)
; template <class Epi, class Sched, bool ALIGN_EPI = false, bool SP2 = false>
; __device__ __forceinline__ void gemm_phase(PG8_LAS unsigned char* lds, const Gemm g, const Sched& S, const Epi& E) {
;     ...
;             PG8_WAIT_V(8); PG8_WAIT_L(0); PG8_BAR; PG8_MMA(1, 0, At, B0); PG8_MMA(1, 1, At, B1); PG8_BAR; PG8_SCHED;
;             PG8_LDB(B0, 1, 0); PG8_LDB(B1, 1, 1); PG8_SCHED; PG8_LDA(At, 1, 0); PG8_STAGE(PG8_SA(0, 1), a2 + hstepA, voffA);
;             PG8_WAIT_V(8); PG8_WAIT_L(0); PG8_BAR; PG8_MMA(0, 0, At, B0); PG8_MMA(0, 1, At, B1); PG8_BAR; PG8_SCHED;
	s_setprio 1
	s_waitcnt lgkmcnt(0)
	v_mfma_f32_16x16x32_bf16 v[60:63], v[138:141], v[170:173], v[60:63]
	v_mfma_f32_16x16x32_bf16 v[56:59], v[146:149], v[170:173], v[56:59]
	v_mfma_f32_16x16x32_bf16 v[52:55], v[138:141], v[178:181], v[52:55]
	v_mfma_f32_16x16x32_bf16 v[48:51], v[146:149], v[178:181], v[48:51]
	v_mfma_f32_16x16x32_bf16 v[36:39], v[138:141], v[192:195], v[36:39]
	v_mfma_f32_16x16x32_bf16 v[32:35], v[146:149], v[192:195], v[32:35]
	v_mfma_f32_16x16x32_bf16 v[20:23], v[138:141], v[234:237], v[20:23]
	v_mfma_f32_16x16x32_bf16 v[16:19], v[146:149], v[234:237], v[16:19]
	v_mfma_f32_16x16x32_bf16 v[60:63], v[142:145], v[174:177], v[60:63]
	v_mfma_f32_16x16x32_bf16 v[56:59], v[150:153], v[174:177], v[56:59]
	v_mfma_f32_16x16x32_bf16 v[52:55], v[142:145], v[182:185], v[52:55]
	v_mfma_f32_16x16x32_bf16 v[48:51], v[150:153], v[182:185], v[48:51]
	v_mfma_f32_16x16x32_bf16 v[36:39], v[142:145], v[230:233], v[36:39]
	v_mfma_f32_16x16x32_bf16 v[32:35], v[150:153], v[230:233], v[32:35]
	v_mfma_f32_16x16x32_bf16 v[20:23], v[142:145], v[238:241], v[20:23]
	v_mfma_f32_16x16x32_bf16 v[16:19], v[150:153], v[238:241], v[16:19]
	s_setprio 0
	s_setprio 1
	v_mfma_f32_16x16x32_bf16 v[44:47], v[154:157], v[170:173], v[44:47]
	v_mfma_f32_16x16x32_bf16 v[40:43], v[162:165], v[170:173], v[40:43]
	v_mfma_f32_16x16x32_bf16 v[28:31], v[154:157], v[178:181], v[28:31]
	v_mfma_f32_16x16x32_bf16 v[24:27], v[162:165], v[178:181], v[24:27]
	v_mfma_f32_16x16x32_bf16 v[12:15], v[154:157], v[192:195], v[12:15]
	v_mfma_f32_16x16x32_bf16 v[8:11], v[162:165], v[192:195], v[8:11]
	v_mfma_f32_16x16x32_bf16 v[4:7], v[154:157], v[234:237], v[4:7]
	v_mfma_f32_16x16x32_bf16 v[0:3], v[162:165], v[234:237], v[0:3]
	v_mfma_f32_16x16x32_bf16 v[44:47], v[158:161], v[174:177], v[44:47]
	v_mfma_f32_16x16x32_bf16 v[40:43], v[166:169], v[174:177], v[40:43]
	v_mfma_f32_16x16x32_bf16 v[28:31], v[158:161], v[182:185], v[28:31]
	v_mfma_f32_16x16x32_bf16 v[24:27], v[166:169], v[182:185], v[24:27]
	v_mfma_f32_16x16x32_bf16 v[12:15], v[158:161], v[230:233], v[12:15]
	v_mfma_f32_16x16x32_bf16 v[8:11], v[166:169], v[230:233], v[8:11]
	v_mfma_f32_16x16x32_bf16 v[4:7], v[158:161], v[238:241], v[4:7]
	v_mfma_f32_16x16x32_bf16 v[0:3], v[166:169], v[238:241], v[0:3]
	s_setprio 0
	s_barrier
	v_add_u32_e32 v150, 0x18000, v136
	v_add_u32_e32 v166, 0x1c000, v136
	ds_read_b128 v[138:141], v150
	ds_read_b128 v[142:145], v150 offset:1024
	ds_read_b128 v[146:149], v150 offset:2048
	ds_read_b128 v[150:153], v150 offset:3072
	ds_read_b128 v[154:157], v166
	ds_read_b128 v[158:161], v166 offset:1024
	ds_read_b128 v[162:165], v166 offset:2048
	ds_read_b128 v[166:169], v166 offset:3072
	ds_read_b128 v[170:173], v137 offset:32768
	ds_read_b128 v[174:177], v137 offset:33792
	ds_read_b128 v[178:181], v137 offset:34816
	ds_read_b128 v[182:185], v137 offset:35840
	ds_read_b128 v[192:195], v137 offset:36864
	ds_read_b128 v[230:233], v137 offset:37888
	ds_read_b128 v[234:237], v137 offset:38912
	ds_read_b128 v[238:241], v137 offset:39936
	s_mov_b32 m0, s53
	v_lshl_add_u64 v[246:247], s[38:39], 0, v[132:133]
	global_load_lds_dwordx4 v[246:247], off
	s_mov_b32 m0, s54
	v_lshl_add_u64 v[246:247], s[38:39], 0, v[130:131]
	global_load_lds_dwordx4 v[246:247], off
	s_waitcnt vmcnt(8)
	s_waitcnt lgkmcnt(0)
	s_barrier
	s_setprio 1
	s_waitcnt lgkmcnt(0)
	v_mfma_f32_16x16x32_bf16 v[124:127], v[138:141], v[170:173], v[124:127]
	v_mfma_f32_16x16x32_bf16 v[120:123], v[146:149], v[170:173], v[120:123]
	v_mfma_f32_16x16x32_bf16 v[116:119], v[138:141], v[178:181], v[116:119]
	v_mfma_f32_16x16x32_bf16 v[112:115], v[146:149], v[178:181], v[112:115]
	v_mfma_f32_16x16x32_bf16 v[100:103], v[138:141], v[192:195], v[100:103]
	v_mfma_f32_16x16x32_bf16 v[96:99], v[146:149], v[192:195], v[96:99]
	v_mfma_f32_16x16x32_bf16 v[84:87], v[138:141], v[234:237], v[84:87]
	v_mfma_f32_16x16x32_bf16 v[80:83], v[146:149], v[234:237], v[80:83]
	v_mfma_f32_16x16x32_bf16 v[124:127], v[142:145], v[174:177], v[124:127]
	v_mfma_f32_16x16x32_bf16 v[120:123], v[150:153], v[174:177], v[120:123]
	v_mfma_f32_16x16x32_bf16 v[116:119], v[142:145], v[182:185], v[116:119]
	v_mfma_f32_16x16x32_bf16 v[112:115], v[150:153], v[182:185], v[112:115]
	v_mfma_f32_16x16x32_bf16 v[100:103], v[142:145], v[230:233], v[100:103]
	v_mfma_f32_16x16x32_bf16 v[96:99], v[150:153], v[230:233], v[96:99]
	v_mfma_f32_16x16x32_bf16 v[84:87], v[142:145], v[238:241], v[84:87]
	v_mfma_f32_16x16x32_bf16 v[80:83], v[150:153], v[238:241], v[80:83]
	s_setprio 0
	s_setprio 1
	v_mfma_f32_16x16x32_bf16 v[108:111], v[154:157], v[170:173], v[108:111]
	v_mfma_f32_16x16x32_bf16 v[104:107], v[162:165], v[170:173], v[104:107]
	v_mfma_f32_16x16x32_bf16 v[92:95], v[154:157], v[178:181], v[92:95]
	v_mfma_f32_16x16x32_bf16 v[88:91], v[162:165], v[178:181], v[88:91]
	v_mfma_f32_16x16x32_bf16 v[76:79], v[154:157], v[192:195], v[76:79]
	v_mfma_f32_16x16x32_bf16 v[72:75], v[162:165], v[192:195], v[72:75]
	v_mfma_f32_16x16x32_bf16 v[68:71], v[154:157], v[234:237], v[68:71]
	v_mfma_f32_16x16x32_bf16 v[64:67], v[162:165], v[234:237], v[64:67]
	v_mfma_f32_16x16x32_bf16 v[108:111], v[158:161], v[174:177], v[108:111]
	v_mfma_f32_16x16x32_bf16 v[104:107], v[166:169], v[174:177], v[104:107]
	v_mfma_f32_16x16x32_bf16 v[92:95], v[158:161], v[182:185], v[92:95]
	v_mfma_f32_16x16x32_bf16 v[88:91], v[166:169], v[182:185], v[88:91]
	v_mfma_f32_16x16x32_bf16 v[76:79], v[158:161], v[230:233], v[76:79]
	v_mfma_f32_16x16x32_bf16 v[72:75], v[166:169], v[230:233], v[72:75]
	v_mfma_f32_16x16x32_bf16 v[68:71], v[158:161], v[238:241], v[68:71]
	v_mfma_f32_16x16x32_bf16 v[64:67], v[166:169], v[238:241], v[64:67]
	s_setprio 0
	s_barrier
; #define PG8_STAGE(bufoff, gbase, voff) do { _Pragma("unroll") for (int _i = 0; _i < 2; ++_i) \
;         __builtin_amdgcn_global_load_lds((const unsigned*)((const char*)(gbase) + (voff)[_i]), (PG8_LAS unsigned*)(lds + (bufoff) + ldsw + _i * 8192), 16, 0, 0); } while (0)
; #define PG8_LDA(dst, b, h) do { _Pragma("unroll") for (int m = 0; m < 4; ++m) _Pragma("unroll") for (int k = 0; k < 2; ++k) dst[m][k] = *(const PG8_LAS bf16x8*)(lds + PG8_SA(b, h) + aoff + m * 2048 + k * 1024); } while (0)
; #define PG8_WAIT_V(n) asm volatile("s_waitcnt vmcnt(" #n ")" ::: "memory")
; template <class Epi, class Sched, bool ALIGN_EPI = false, bool SP2 = false>
; __device__ __forceinline__ void gemm_phase(PG8_LAS unsigned char* lds, const Gemm g, const Sched& S, const Epi& E) {
;     ...
;             PG8_LDA(At, 1, 1); PG8_STAGE(PG8_SB(1, 0), b3, voffB); PG8_STAGE(PG8_SB(1, 1), b3 + hstepB, voffB); PG8_STAGE(PG8_SA(1, 0), a3, voffA);
;             PG8_WAIT_V(8); PG8_WAIT_L(0); PG8_BAR; PG8_MMA(1, 0, At, B0); PG8_MMA(1, 1, At, B1); PG8_BAR; PG8_SCHED;
;             } else {
;             PG8_LDB(B0, 0, 0); PG8_SCHED; PG8_LDA(At, 0, 0); PG8_STAGE(PG8_SA(1, 1), a1 + hstepA, voffA);
;             PG8_WAIT_L(8); PG8_BAR; PG8_WAIT_L(0); PG8_MMA(0, 0, At, B0); PG8_BAR; PG8_SCHED;
;             PG8_LDB(B1, 0, 1); PG8_STAGE(PG8_SB(0, 0), b2, voffB);
;             PG8_BAR; PG8_WAIT_L(0); PG8_MMA(0, 1, At, B1); PG8_BAR;
;             PG8_LDA(At, 0, 1); PG8_STAGE(PG8_SA(0, 0), a2, voffA);
;             PG8_BAR; PG8_WAIT_L(0); PG8_MMA(1, 0, At, B0); PG8_BAR; PG8_SCHED;
;             PG8_STAGE(PG8_SB(0, 1), b2 + hstepB, voffB);
;             PG8_WAIT_V(6); PG8_BAR; PG8_MMA(1, 1, At, B1); PG8_BAR;
;             PG8_LDB(B0, 1, 0); PG8_SCHED; PG8_LDA(At, 1, 0); PG8_STAGE(PG8_SA(0, 1), a2 + hstepA, voffA);
;             PG8_WAIT_L(8); PG8_BAR; PG8_WAIT_L(0); PG8_MMA(0, 0, At, B0); PG8_BAR; PG8_SCHED;
;             PG8_LDB(B1, 1, 1); PG8_STAGE(PG8_SB(1, 0), b3, voffB);
;             PG8_BAR; PG8_WAIT_L(0); PG8_MMA(0, 1, At, B1); PG8_BAR;
;             PG8_LDA(At, 1, 1); PG8_STAGE(PG8_SA(1, 0), a3, voffA);
;             PG8_BAR; PG8_WAIT_L(0); PG8_MMA(1, 0, At, B0); PG8_BAR; PG8_SCHED;
;             PG8_STAGE(PG8_SB(1, 1), b3 + hstepB, voffB);
;             PG8_WAIT_V(6); PG8_BAR; PG8_MMA(1, 1, At, B1); PG8_BAR;
;             }
;         }
;         if constexpr (ALIGN_EPI) { if (wr == 0) PG8_BAR; }
	ds_read_b128 v[170:173], v137 offset:49152
	ds_read_b128 v[174:177], v137 offset:50176
	ds_read_b128 v[178:181], v137 offset:51200
	ds_read_b128 v[182:185], v137 offset:52224
	ds_read_b128 v[192:195], v137 offset:53248
	ds_read_b128 v[230:233], v137 offset:54272
	ds_read_b128 v[234:237], v137 offset:55296
	ds_read_b128 v[238:241], v137 offset:56320
	s_mov_b32 m0, s65
	v_lshl_add_u64 v[186:187], v[186:187], 0, s[94:95]
	global_load_lds_dwordx4 v[186:187], off
	s_mov_b32 m0, s64
	v_lshl_add_u64 v[186:187], v[196:197], 0, s[94:95]
	global_load_lds_dwordx4 v[186:187], off
	s_mov_b32 m0, s73
	v_lshl_add_u64 v[186:187], s[36:37], 0, v[188:189]
	global_load_lds_dwordx4 v[186:187], off
	s_mov_b32 m0, s72
	v_lshl_add_u64 v[186:187], s[36:37], 0, v[128:129]
	global_load_lds_dwordx4 v[186:187], off
	s_mov_b32 m0, s56
	v_lshl_add_u64 v[186:187], v[242:243], 0, s[94:95]
	global_load_lds_dwordx4 v[186:187], off
	s_mov_b32 m0, s57
	v_lshl_add_u64 v[186:187], v[244:245], 0, s[94:95]
	global_load_lds_dwordx4 v[186:187], off
	s_waitcnt vmcnt(8)
	s_waitcnt lgkmcnt(0)
	s_barrier
	s_setprio 1
	s_waitcnt lgkmcnt(0)
	v_mfma_f32_16x16x32_bf16 v[60:63], v[138:141], v[170:173], v[60:63]
	v_mfma_f32_16x16x32_bf16 v[56:59], v[146:149], v[170:173], v[56:59]
	v_mfma_f32_16x16x32_bf16 v[52:55], v[138:141], v[178:181], v[52:55]
	v_mfma_f32_16x16x32_bf16 v[48:51], v[146:149], v[178:181], v[48:51]
	v_mfma_f32_16x16x32_bf16 v[36:39], v[138:141], v[192:195], v[36:39]
	v_mfma_f32_16x16x32_bf16 v[32:35], v[146:149], v[192:195], v[32:35]
	v_mfma_f32_16x16x32_bf16 v[20:23], v[138:141], v[234:237], v[20:23]
	v_mfma_f32_16x16x32_bf16 v[16:19], v[146:149], v[234:237], v[16:19]
	v_mfma_f32_16x16x32_bf16 v[60:63], v[142:145], v[174:177], v[60:63]
	v_mfma_f32_16x16x32_bf16 v[56:59], v[150:153], v[174:177], v[56:59]
	v_mfma_f32_16x16x32_bf16 v[52:55], v[142:145], v[182:185], v[52:55]
	v_mfma_f32_16x16x32_bf16 v[48:51], v[150:153], v[182:185], v[48:51]
	v_mfma_f32_16x16x32_bf16 v[36:39], v[142:145], v[230:233], v[36:39]
	v_mfma_f32_16x16x32_bf16 v[32:35], v[150:153], v[230:233], v[32:35]
	v_mfma_f32_16x16x32_bf16 v[20:23], v[142:145], v[238:241], v[20:23]
	v_mfma_f32_16x16x32_bf16 v[16:19], v[150:153], v[238:241], v[16:19]
	s_setprio 0
	s_setprio 1
	v_mfma_f32_16x16x32_bf16 v[44:47], v[154:157], v[170:173], v[44:47]
	v_mfma_f32_16x16x32_bf16 v[40:43], v[162:165], v[170:173], v[40:43]
	v_mfma_f32_16x16x32_bf16 v[28:31], v[154:157], v[178:181], v[28:31]
	v_mfma_f32_16x16x32_bf16 v[24:27], v[162:165], v[178:181], v[24:27]
	v_mfma_f32_16x16x32_bf16 v[12:15], v[154:157], v[192:195], v[12:15]
	v_mfma_f32_16x16x32_bf16 v[8:11], v[162:165], v[192:195], v[8:11]
	v_mfma_f32_16x16x32_bf16 v[4:7], v[154:157], v[234:237], v[4:7]
	v_mfma_f32_16x16x32_bf16 v[0:3], v[162:165], v[234:237], v[0:3]
	v_mfma_f32_16x16x32_bf16 v[44:47], v[158:161], v[174:177], v[44:47]
	v_mfma_f32_16x16x32_bf16 v[40:43], v[166:169], v[174:177], v[40:43]
	v_mfma_f32_16x16x32_bf16 v[28:31], v[158:161], v[182:185], v[28:31]
	v_mfma_f32_16x16x32_bf16 v[24:27], v[166:169], v[182:185], v[24:27]
	v_mfma_f32_16x16x32_bf16 v[12:15], v[158:161], v[230:233], v[12:15]
	v_mfma_f32_16x16x32_bf16 v[8:11], v[166:169], v[230:233], v[8:11]
	v_mfma_f32_16x16x32_bf16 v[4:7], v[158:161], v[238:241], v[4:7]
	v_mfma_f32_16x16x32_bf16 v[0:3], v[166:169], v[238:241], v[0:3]
	s_setprio 0
	s_andn2_b64 vcc, exec, s[8:9]
	s_mov_b64 s[36:37], -1
	s_mov_b64 s[8:9], 0
	s_mov_b64 s[38:39], 0x100
	s_barrier
	s_cbranch_vccz .LBB0_901
	s_and_b64 vcc, exec, s[20:21]
	s_cbranch_vccz .LBB0_904
	s_barrier

; #define PG8_STAGE(bufoff, gbase, voff) do { _Pragma("unroll") for (int _i = 0; _i < 2; ++_i) \
;         __builtin_amdgcn_global_load_lds((const unsigned*)((const char*)(gbase) + (voff)[_i]), (PG8_LAS unsigned*)(lds + (bufoff) + ldsw + _i * 8192), 16, 0, 0); } while (0)
; #define PG8_LDA(dst, b, h) do { _Pragma("unroll") for (int m = 0; m < 4; ++m) _Pragma("unroll") for (int k = 0; k < 2; ++k) dst[m][k] = *(const PG8_LAS bf16x8*)(lds + PG8_SA(b, h) + aoff + m * 2048 + k * 1024); } while (0)
; #define PG8_LDB(dst, b, h) do { _Pragma("unroll") for (int n = 0; n < 2; ++n) _Pragma("unroll") for (int k = 0; k < 2; ++k) dst[n][k] = *(const PG8_LAS bf16x8*)(lds + PG8_SB(b, h) + boff + n * 2048 + k * 1024); } while (0)
; #define PG8_MMA(ai, bj, At, Bt) do { __builtin_amdgcn_s_setprio(1); _Pragma("unroll") for (int m = 0; m < 4; ++m) _Pragma("unroll") for (int n = 0; n < 2; ++n) _Pragma("unroll") for (int k = 0; k < 2; ++k) \
;         acc[ai][bj][m][n] = __builtin_amdgcn_mfma_f32_16x16x32_bf16(Bt[n][k], At[m][k], acc[ai][bj][m][n], 0, 0, 0); __builtin_amdgcn_s_setprio(0); } while (0)
; #define PG8_WAIT_V(n) asm volatile("s_waitcnt vmcnt(" #n ")" ::: "memory")
; #define PG8_WAIT_L(n) asm volatile("s_waitcnt lgkmcnt(" #n ")" ::: "memory")
; #define PG8_BAR __builtin_amdgcn_s_barrier()
; #define PG8_SCHED __builtin_amdgcn_sched_barrier(0)
; template <class Epi, class Sched, bool ALIGN_EPI = false, bool SP2 = false>
; __device__ __forceinline__ void gemm_phase(PG8_LAS unsigned char* lds, const Gemm g, const Sched& S, const Epi& E) {
;     ...
;             PG8_LDB(B0, 0, 0); PG8_LDB(B1, 0, 1); PG8_SCHED; PG8_LDA(At, 0, 0); PG8_STAGE(PG8_SA(1, 1), a1 + hstepA, voffA);
;             PG8_WAIT_V(8); PG8_WAIT_L(0); PG8_BAR; PG8_MMA(0, 0, At, B0); PG8_MMA(0, 1, At, B1); PG8_BAR; PG8_SCHED;
;             PG8_LDA(At, 0, 1); PG8_STAGE(PG8_SB(0, 0), b2, voffB); PG8_STAGE(PG8_SB(0, 1), b2 + hstepB, voffB); PG8_STAGE(PG8_SA(0, 0), a2, voffA);
;             PG8_WAIT_V(8); PG8_WAIT_L(0); PG8_BAR; PG8_MMA(1, 0, At, B0); PG8_MMA(1, 1, At, B1); PG8_BAR; PG8_SCHED;
.LBB0_1642:
	v_add_u32_e32 v150, 0x10000, v148
	v_add_u32_e32 v166, 0x14000, v148
	ds_read_b128 v[128:131], v150
	ds_read_b128 v[138:141], v150 offset:1024
	ds_read_b128 v[142:145], v150 offset:2048
	ds_read_b128 v[150:153], v150 offset:3072
	ds_read_b128 v[154:157], v166
	ds_read_b128 v[158:161], v166 offset:1024
	ds_read_b128 v[162:165], v166 offset:2048
	ds_read_b128 v[166:169], v166 offset:3072
	ds_read_b128 v[170:173], v149
	ds_read_b128 v[174:177], v149 offset:1024
	ds_read_b128 v[178:181], v149 offset:2048
	ds_read_b128 v[182:185], v149 offset:3072
	ds_read_b128 v[192:195], v149 offset:4096
	ds_read_b128 v[230:233], v149 offset:5120
	ds_read_b128 v[234:237], v149 offset:6144
	ds_read_b128 v[238:241], v149 offset:7168
	s_add_i32 s74, s28, 2
	s_add_u32 s75, s26, 0x80
	s_addc_u32 s29, s27, 0
	s_add_i32 s78, 0, 0x10000
	s_cmp_eq_u32 s54, s28
	s_cselect_b32 s29, s9, s29
	s_cselect_b32 s28, s8, s75
	s_cselect_b32 s77, s25, s73
	s_cselect_b32 s76, s24, s72
	s_add_i32 s75, 0, 0x14000
	s_add_i32 m0, s36, 0xc000
	v_lshl_add_u64 v[186:187], s[26:27], 0, v[134:135]
	global_load_lds_dwordx4 v[186:187], off
	s_add_i32 m0, s36, 0xe000
	v_lshl_add_u64 v[186:187], s[26:27], 0, v[136:137]
	global_load_lds_dwordx4 v[186:187], off
	s_waitcnt vmcnt(8)
	s_waitcnt lgkmcnt(0)
	s_barrier
	s_setprio 1
	s_waitcnt lgkmcnt(0)
	v_mfma_f32_16x16x32_bf16 v[124:127], v[128:131], v[170:173], v[124:127]
	v_mfma_f32_16x16x32_bf16 v[96:99], v[142:145], v[170:173], v[96:99]
	v_mfma_f32_16x16x32_bf16 v[120:123], v[128:131], v[178:181], v[120:123]
	v_mfma_f32_16x16x32_bf16 v[92:95], v[142:145], v[178:181], v[92:95]
	v_mfma_f32_16x16x32_bf16 v[116:119], v[128:131], v[192:195], v[116:119]
	v_mfma_f32_16x16x32_bf16 v[88:91], v[142:145], v[192:195], v[88:91]
	v_mfma_f32_16x16x32_bf16 v[112:115], v[128:131], v[234:237], v[112:115]
	v_mfma_f32_16x16x32_bf16 v[80:83], v[142:145], v[234:237], v[80:83]
	v_mfma_f32_16x16x32_bf16 v[124:127], v[138:141], v[174:177], v[124:127]
	v_mfma_f32_16x16x32_bf16 v[96:99], v[150:153], v[174:177], v[96:99]
	v_mfma_f32_16x16x32_bf16 v[120:123], v[138:141], v[182:185], v[120:123]
	v_mfma_f32_16x16x32_bf16 v[92:95], v[150:153], v[182:185], v[92:95]
	v_mfma_f32_16x16x32_bf16 v[116:119], v[138:141], v[230:233], v[116:119]
	v_mfma_f32_16x16x32_bf16 v[88:91], v[150:153], v[230:233], v[88:91]
	v_mfma_f32_16x16x32_bf16 v[112:115], v[138:141], v[238:241], v[112:115]
	v_mfma_f32_16x16x32_bf16 v[80:83], v[150:153], v[238:241], v[80:83]
	s_setprio 0
	s_setprio 1
	v_mfma_f32_16x16x32_bf16 v[72:75], v[154:157], v[170:173], v[72:75]
	v_mfma_f32_16x16x32_bf16 v[44:47], v[162:165], v[170:173], v[44:47]
	v_mfma_f32_16x16x32_bf16 v[64:67], v[154:157], v[178:181], v[64:67]
	v_mfma_f32_16x16x32_bf16 v[36:39], v[162:165], v[178:181], v[36:39]
	v_mfma_f32_16x16x32_bf16 v[56:59], v[154:157], v[192:195], v[56:59]
	v_mfma_f32_16x16x32_bf16 v[28:31], v[162:165], v[192:195], v[28:31]
	v_mfma_f32_16x16x32_bf16 v[48:51], v[154:157], v[234:237], v[48:51]
	v_mfma_f32_16x16x32_bf16 v[20:23], v[162:165], v[234:237], v[20:23]
	v_mfma_f32_16x16x32_bf16 v[72:75], v[158:161], v[174:177], v[72:75]
	v_mfma_f32_16x16x32_bf16 v[44:47], v[166:169], v[174:177], v[44:47]
	v_mfma_f32_16x16x32_bf16 v[64:67], v[158:161], v[182:185], v[64:67]
	v_mfma_f32_16x16x32_bf16 v[36:39], v[166:169], v[182:185], v[36:39]
	v_mfma_f32_16x16x32_bf16 v[56:59], v[158:161], v[230:233], v[56:59]
	v_mfma_f32_16x16x32_bf16 v[28:31], v[166:169], v[230:233], v[28:31]
	v_mfma_f32_16x16x32_bf16 v[48:51], v[158:161], v[238:241], v[48:51]
	v_mfma_f32_16x16x32_bf16 v[20:23], v[166:169], v[238:241], v[20:23]
	s_setprio 0
	s_barrier
	ds_read_b128 v[170:173], v149 offset:16384
	ds_read_b128 v[174:177], v149 offset:17408
	ds_read_b128 v[178:181], v149 offset:18432
	ds_read_b128 v[182:185], v149 offset:19456
	ds_read_b128 v[192:195], v149 offset:20480
	ds_read_b128 v[230:233], v149 offset:21504
	ds_read_b128 v[234:237], v149 offset:22528
	ds_read_b128 v[238:241], v149 offset:23552
	s_add_i32 s78, s78, s30
	s_mov_b32 m0, s78
	v_lshl_add_u64 v[186:187], s[76:77], 0, v[188:189]
	global_load_lds_dwordx4 v[186:187], off
	s_add_i32 m0, s78, 0x2000
	v_lshl_add_u64 v[196:197], s[76:77], 0, v[132:133]
	s_add_u32 s76, s76, s44
	s_addc_u32 s77, s77, 0
	s_add_i32 s75, s75, s30
	global_load_lds_dwordx4 v[196:197], off
	v_lshl_add_u64 v[242:243], s[76:77], 0, v[188:189]
	s_mov_b32 m0, s75
	v_lshl_add_u64 v[244:245], s[76:77], 0, v[132:133]
	global_load_lds_dwordx4 v[242:243], off
	s_add_i32 m0, s75, 0x2000
	v_lshl_add_u64 v[246:247], s[28:29], 0, v[188:189]
	global_load_lds_dwordx4 v[244:245], off
	s_mov_b32 m0, s36
	v_lshl_add_u64 v[248:249], s[28:29], 0, v[132:133]
	global_load_lds_dwordx4 v[246:247], off
	s_mov_b32 m0, s37
	s_nop 0
	global_load_lds_dwordx4 v[248:249], off
	s_waitcnt vmcnt(8)
	s_waitcnt lgkmcnt(0)
	s_barrier
; #define PG8_STAGE(bufoff, gbase, voff) do { _Pragma("unroll") for (int _i = 0; _i < 2; ++_i) \
;         __builtin_amdgcn_global_load_lds((const unsigned*)((const char*)(gbase) + (voff)[_i]), (PG8_LAS unsigned*)(lds + (bufoff) + ldsw + _i * 8192), 16, 0, 0); } while (0)
; #define PG8_LDA(dst, b, h) do { _Pragma("unroll") for (int m = 0; m < 4; ++m) _Pragma("unroll") for (int k = 0; k < 2; ++k) dst[m][k] = *(const PG8_LAS bf16x8*)(lds + PG8_SA(b, h) + aoff + m * 2048 + k * 1024); } while (0)
; #define PG8_LDB(dst, b, h) do { _Pragma("unroll") for (int n = 0; n < 2; ++n) _Pragma("unroll") for (int k = 0; k < 2; ++k) dst[n][k] = *(const PG8_LAS bf16x8*)(lds + PG8_SB(b, h) + boff + n * 2048 + k * 1024); } while (0)
; #define PG8_MMA(ai, bj, At, Bt) do { __builtin_amdgcn_s_setprio(1); _Pragma("unroll") for (int m = 0; m < 4; ++m) _Pragma("unroll") for (int n = 0; n < 2; ++n) _Pragma("unroll") for (int k = 0; k < 2; ++k) \
;         acc[ai][bj][m][n] = __builtin_amdgcn_mfma_f32_16x16x32_bf16(Bt[n][k], At[m][k], acc[ai][bj][m][n], 0, 0, 0); __builtin_amdgcn_s_setprio(0); } while (0)
; #define PG8_WAIT_V(n) asm volatile("s_waitcnt vmcnt(" #n ")" ::: "memory")
; #define PG8_WAIT_L(n) asm volatile("s_waitcnt lgkmcnt(" #n ")" ::: "memory")
; #define PG8_BAR __builtin_amdgcn_s_barrier()
; #define PG8_SCHED __builtin_amdgcn_sched_barrier(0)
; template <class Epi, class Sched, bool ALIGN_EPI = false, bool SP2 = false>
; __device__ __forceinline__ void gemm_phase(PG8_LAS unsigned char* lds, const Gemm g, const Sched& S, const Epi& E) {
;     ...
;             PG8_WAIT_V(8); PG8_WAIT_L(0); PG8_BAR; PG8_MMA(1, 0, At, B0); PG8_MMA(1, 1, At, B1); PG8_BAR; PG8_SCHED;
;             PG8_LDB(B0, 1, 0); PG8_LDB(B1, 1, 1); PG8_SCHED; PG8_LDA(At, 1, 0); PG8_STAGE(PG8_SA(0, 1), a2 + hstepA, voffA);
;             PG8_WAIT_V(8); PG8_WAIT_L(0); PG8_BAR; PG8_MMA(0, 0, At, B0); PG8_MMA(0, 1, At, B1); PG8_BAR; PG8_SCHED;
	s_setprio 1
	s_waitcnt lgkmcnt(0)
	v_mfma_f32_16x16x32_bf16 v[108:111], v[128:131], v[170:173], v[108:111]
	v_mfma_f32_16x16x32_bf16 v[76:79], v[142:145], v[170:173], v[76:79]
	v_mfma_f32_16x16x32_bf16 v[104:107], v[128:131], v[178:181], v[104:107]
	v_mfma_f32_16x16x32_bf16 v[68:71], v[142:145], v[178:181], v[68:71]
	v_mfma_f32_16x16x32_bf16 v[100:103], v[128:131], v[192:195], v[100:103]
	v_mfma_f32_16x16x32_bf16 v[60:63], v[142:145], v[192:195], v[60:63]
	v_mfma_f32_16x16x32_bf16 v[84:87], v[128:131], v[234:237], v[84:87]
	v_mfma_f32_16x16x32_bf16 v[52:55], v[142:145], v[234:237], v[52:55]
	v_mfma_f32_16x16x32_bf16 v[108:111], v[138:141], v[174:177], v[108:111]
	v_mfma_f32_16x16x32_bf16 v[76:79], v[150:153], v[174:177], v[76:79]
	v_mfma_f32_16x16x32_bf16 v[104:107], v[138:141], v[182:185], v[104:107]
	v_mfma_f32_16x16x32_bf16 v[68:71], v[150:153], v[182:185], v[68:71]
	v_mfma_f32_16x16x32_bf16 v[100:103], v[138:141], v[230:233], v[100:103]
	v_mfma_f32_16x16x32_bf16 v[60:63], v[150:153], v[230:233], v[60:63]
	v_mfma_f32_16x16x32_bf16 v[84:87], v[138:141], v[238:241], v[84:87]
	v_mfma_f32_16x16x32_bf16 v[52:55], v[150:153], v[238:241], v[52:55]
	s_setprio 0
	s_setprio 1
	v_mfma_f32_16x16x32_bf16 v[40:43], v[154:157], v[170:173], v[40:43]
	v_mfma_f32_16x16x32_bf16 v[12:15], v[162:165], v[170:173], v[12:15]
	v_mfma_f32_16x16x32_bf16 v[32:35], v[154:157], v[178:181], v[32:35]
	v_mfma_f32_16x16x32_bf16 v[8:11], v[162:165], v[178:181], v[8:11]
	v_mfma_f32_16x16x32_bf16 v[24:27], v[154:157], v[192:195], v[24:27]
	v_mfma_f32_16x16x32_bf16 v[4:7], v[162:165], v[192:195], v[4:7]
	v_mfma_f32_16x16x32_bf16 v[16:19], v[154:157], v[234:237], v[16:19]
	v_mfma_f32_16x16x32_bf16 v[0:3], v[162:165], v[234:237], v[0:3]
	v_mfma_f32_16x16x32_bf16 v[40:43], v[158:161], v[174:177], v[40:43]
	v_mfma_f32_16x16x32_bf16 v[12:15], v[166:169], v[174:177], v[12:15]
	v_mfma_f32_16x16x32_bf16 v[32:35], v[158:161], v[182:185], v[32:35]
	v_mfma_f32_16x16x32_bf16 v[8:11], v[166:169], v[182:185], v[8:11]
	v_mfma_f32_16x16x32_bf16 v[24:27], v[158:161], v[230:233], v[24:27]
	v_mfma_f32_16x16x32_bf16 v[4:7], v[166:169], v[230:233], v[4:7]
	v_mfma_f32_16x16x32_bf16 v[16:19], v[158:161], v[238:241], v[16:19]
	v_mfma_f32_16x16x32_bf16 v[0:3], v[166:169], v[238:241], v[0:3]
	s_setprio 0
	s_barrier
	v_add_u32_e32 v150, 0x18000, v148
	v_add_u32_e32 v166, 0x1c000, v148
	ds_read_b128 v[128:131], v150
	ds_read_b128 v[138:141], v150 offset:1024
	ds_read_b128 v[142:145], v150 offset:2048
	ds_read_b128 v[150:153], v150 offset:3072
	ds_read_b128 v[154:157], v166
	ds_read_b128 v[158:161], v166 offset:1024
	ds_read_b128 v[162:165], v166 offset:2048
	ds_read_b128 v[166:169], v166 offset:3072
	ds_read_b128 v[170:173], v149 offset:32768
	ds_read_b128 v[174:177], v149 offset:33792
	ds_read_b128 v[178:181], v149 offset:34816
	ds_read_b128 v[182:185], v149 offset:35840
	ds_read_b128 v[192:195], v149 offset:36864
	ds_read_b128 v[230:233], v149 offset:37888
	ds_read_b128 v[234:237], v149 offset:38912
	ds_read_b128 v[238:241], v149 offset:39936
	s_add_i32 s75, 0, 0x18000
	s_add_i32 s76, 0, 0x1c000
	s_add_u32 s28, s28, s44
	s_addc_u32 s29, s29, 0
	s_mov_b32 m0, s46
	v_lshl_add_u64 v[250:251], s[28:29], 0, v[188:189]
	global_load_lds_dwordx4 v[250:251], off
	s_mov_b32 m0, s47
	v_lshl_add_u64 v[250:251], s[28:29], 0, v[132:133]
	global_load_lds_dwordx4 v[250:251], off
	s_waitcnt vmcnt(8)
	s_waitcnt lgkmcnt(0)
	s_barrier
	s_setprio 1
	s_waitcnt lgkmcnt(0)
	v_mfma_f32_16x16x32_bf16 v[124:127], v[128:131], v[170:173], v[124:127]
	v_mfma_f32_16x16x32_bf16 v[96:99], v[142:145], v[170:173], v[96:99]
	v_mfma_f32_16x16x32_bf16 v[120:123], v[128:131], v[178:181], v[120:123]
	v_mfma_f32_16x16x32_bf16 v[92:95], v[142:145], v[178:181], v[92:95]
	v_mfma_f32_16x16x32_bf16 v[116:119], v[128:131], v[192:195], v[116:119]
	v_mfma_f32_16x16x32_bf16 v[88:91], v[142:145], v[192:195], v[88:91]
	v_mfma_f32_16x16x32_bf16 v[112:115], v[128:131], v[234:237], v[112:115]
	v_mfma_f32_16x16x32_bf16 v[80:83], v[142:145], v[234:237], v[80:83]
	v_mfma_f32_16x16x32_bf16 v[124:127], v[138:141], v[174:177], v[124:127]
	v_mfma_f32_16x16x32_bf16 v[96:99], v[150:153], v[174:177], v[96:99]
	v_mfma_f32_16x16x32_bf16 v[120:123], v[138:141], v[182:185], v[120:123]
	v_mfma_f32_16x16x32_bf16 v[92:95], v[150:153], v[182:185], v[92:95]
	v_mfma_f32_16x16x32_bf16 v[116:119], v[138:141], v[230:233], v[116:119]
	v_mfma_f32_16x16x32_bf16 v[88:91], v[150:153], v[230:233], v[88:91]
	v_mfma_f32_16x16x32_bf16 v[112:115], v[138:141], v[238:241], v[112:115]
	v_mfma_f32_16x16x32_bf16 v[80:83], v[150:153], v[238:241], v[80:83]
	s_setprio 0
	s_setprio 1
	v_mfma_f32_16x16x32_bf16 v[72:75], v[154:157], v[170:173], v[72:75]
	v_mfma_f32_16x16x32_bf16 v[44:47], v[162:165], v[170:173], v[44:47]
	v_mfma_f32_16x16x32_bf16 v[64:67], v[154:157], v[178:181], v[64:67]
	v_mfma_f32_16x16x32_bf16 v[36:39], v[162:165], v[178:181], v[36:39]
	v_mfma_f32_16x16x32_bf16 v[56:59], v[154:157], v[192:195], v[56:59]
	v_mfma_f32_16x16x32_bf16 v[28:31], v[162:165], v[192:195], v[28:31]
	v_mfma_f32_16x16x32_bf16 v[48:51], v[154:157], v[234:237], v[48:51]
	v_mfma_f32_16x16x32_bf16 v[20:23], v[162:165], v[234:237], v[20:23]
	v_mfma_f32_16x16x32_bf16 v[72:75], v[158:161], v[174:177], v[72:75]
	v_mfma_f32_16x16x32_bf16 v[44:47], v[166:169], v[174:177], v[44:47]
	v_mfma_f32_16x16x32_bf16 v[64:67], v[158:161], v[182:185], v[64:67]
	v_mfma_f32_16x16x32_bf16 v[36:39], v[166:169], v[182:185], v[36:39]
	v_mfma_f32_16x16x32_bf16 v[56:59], v[158:161], v[230:233], v[56:59]
	v_mfma_f32_16x16x32_bf16 v[28:31], v[166:169], v[230:233], v[28:31]
	v_mfma_f32_16x16x32_bf16 v[48:51], v[158:161], v[238:241], v[48:51]
	v_mfma_f32_16x16x32_bf16 v[20:23], v[166:169], v[238:241], v[20:23]
	s_setprio 0
	s_barrier
; #define PG8_STAGE(bufoff, gbase, voff) do { _Pragma("unroll") for (int _i = 0; _i < 2; ++_i) \
;         __builtin_amdgcn_global_load_lds((const unsigned*)((const char*)(gbase) + (voff)[_i]), (PG8_LAS unsigned*)(lds + (bufoff) + ldsw + _i * 8192), 16, 0, 0); } while (0)
; #define PG8_LDA(dst, b, h) do { _Pragma("unroll") for (int m = 0; m < 4; ++m) _Pragma("unroll") for (int k = 0; k < 2; ++k) dst[m][k] = *(const PG8_LAS bf16x8*)(lds + PG8_SA(b, h) + aoff + m * 2048 + k * 1024); } while (0)
; #define PG8_WAIT_V(n) asm volatile("s_waitcnt vmcnt(" #n ")" ::: "memory")
; template <class Epi, class Sched, bool ALIGN_EPI = false, bool SP2 = false>
; __device__ __forceinline__ void gemm_phase(PG8_LAS unsigned char* lds, const Gemm g, const Sched& S, const Epi& E) {
;     ...
;             PG8_LDA(At, 1, 1); PG8_STAGE(PG8_SB(1, 0), b3, voffB); PG8_STAGE(PG8_SB(1, 1), b3 + hstepB, voffB); PG8_STAGE(PG8_SA(1, 0), a3, voffA);
;             PG8_WAIT_V(8); PG8_WAIT_L(0); PG8_BAR; PG8_MMA(1, 0, At, B0); PG8_MMA(1, 1, At, B1); PG8_BAR; PG8_SCHED;
;             } else {
;             PG8_LDB(B0, 0, 0); PG8_SCHED; PG8_LDA(At, 0, 0); PG8_STAGE(PG8_SA(1, 1), a1 + hstepA, voffA);
;             PG8_WAIT_L(8); PG8_BAR; PG8_WAIT_L(0); PG8_MMA(0, 0, At, B0); PG8_BAR; PG8_SCHED;
;             PG8_LDB(B1, 0, 1); PG8_STAGE(PG8_SB(0, 0), b2, voffB);
;             PG8_BAR; PG8_WAIT_L(0); PG8_MMA(0, 1, At, B1); PG8_BAR;
;             PG8_LDA(At, 0, 1); PG8_STAGE(PG8_SA(0, 0), a2, voffA);
;             PG8_BAR; PG8_WAIT_L(0); PG8_MMA(1, 0, At, B0); PG8_BAR; PG8_SCHED;
;             PG8_STAGE(PG8_SB(0, 1), b2 + hstepB, voffB);
;             PG8_WAIT_V(6); PG8_BAR; PG8_MMA(1, 1, At, B1); PG8_BAR;
;             PG8_LDB(B0, 1, 0); PG8_SCHED; PG8_LDA(At, 1, 0); PG8_STAGE(PG8_SA(0, 1), a2 + hstepA, voffA);
;             PG8_WAIT_L(8); PG8_BAR; PG8_WAIT_L(0); PG8_MMA(0, 0, At, B0); PG8_BAR; PG8_SCHED;
;             PG8_LDB(B1, 1, 1); PG8_STAGE(PG8_SB(1, 0), b3, voffB);
;             PG8_BAR; PG8_WAIT_L(0); PG8_MMA(0, 1, At, B1); PG8_BAR;
;             PG8_LDA(At, 1, 1); PG8_STAGE(PG8_SA(1, 0), a3, voffA);
;             PG8_BAR; PG8_WAIT_L(0); PG8_MMA(1, 0, At, B0); PG8_BAR; PG8_SCHED;
;             PG8_STAGE(PG8_SB(1, 1), b3 + hstepB, voffB);
;             PG8_WAIT_V(6); PG8_BAR; PG8_MMA(1, 1, At, B1); PG8_BAR;
;             }
;         }
;         if constexpr (ALIGN_EPI) { if (wr == 0) PG8_BAR; }
	ds_read_b128 v[170:173], v149 offset:49152
	ds_read_b128 v[174:177], v149 offset:50176
	ds_read_b128 v[178:181], v149 offset:51200
	ds_read_b128 v[182:185], v149 offset:52224
	ds_read_b128 v[192:195], v149 offset:53248
	ds_read_b128 v[230:233], v149 offset:54272
	ds_read_b128 v[234:237], v149 offset:55296
	ds_read_b128 v[238:241], v149 offset:56320
	s_add_i32 s28, s75, s30
	s_mov_b32 m0, s28
	v_lshl_add_u64 v[186:187], v[186:187], 0, s[94:95]
	global_load_lds_dwordx4 v[186:187], off
	v_lshl_add_u64 v[186:187], v[196:197], 0, s[94:95]
	s_add_i32 m0, s28, 0x2000
	s_add_i32 s28, s76, s30
	global_load_lds_dwordx4 v[186:187], off
	s_mov_b32 m0, s28
	v_lshl_add_u64 v[186:187], v[242:243], 0, s[94:95]
	global_load_lds_dwordx4 v[186:187], off
	s_add_i32 m0, s28, 0x2000
	v_lshl_add_u64 v[186:187], v[244:245], 0, s[94:95]
	global_load_lds_dwordx4 v[186:187], off
	s_mov_b32 m0, s62
	v_lshl_add_u64 v[186:187], v[246:247], 0, s[94:95]
	global_load_lds_dwordx4 v[186:187], off
	s_mov_b32 m0, s63
	v_lshl_add_u64 v[186:187], v[248:249], 0, s[94:95]
	global_load_lds_dwordx4 v[186:187], off
	s_waitcnt vmcnt(8)
	s_waitcnt lgkmcnt(0)
	s_barrier
	s_setprio 1
	s_waitcnt lgkmcnt(0)
	v_mfma_f32_16x16x32_bf16 v[108:111], v[128:131], v[170:173], v[108:111]
	v_mfma_f32_16x16x32_bf16 v[76:79], v[142:145], v[170:173], v[76:79]
	v_mfma_f32_16x16x32_bf16 v[104:107], v[128:131], v[178:181], v[104:107]
	v_mfma_f32_16x16x32_bf16 v[68:71], v[142:145], v[178:181], v[68:71]
	v_mfma_f32_16x16x32_bf16 v[100:103], v[128:131], v[192:195], v[100:103]
	v_mfma_f32_16x16x32_bf16 v[60:63], v[142:145], v[192:195], v[60:63]
	v_mfma_f32_16x16x32_bf16 v[84:87], v[128:131], v[234:237], v[84:87]
	v_mfma_f32_16x16x32_bf16 v[52:55], v[142:145], v[234:237], v[52:55]
	v_mfma_f32_16x16x32_bf16 v[108:111], v[138:141], v[174:177], v[108:111]
	v_mfma_f32_16x16x32_bf16 v[76:79], v[150:153], v[174:177], v[76:79]
	v_mfma_f32_16x16x32_bf16 v[104:107], v[138:141], v[182:185], v[104:107]
	v_mfma_f32_16x16x32_bf16 v[68:71], v[150:153], v[182:185], v[68:71]
	v_mfma_f32_16x16x32_bf16 v[100:103], v[138:141], v[230:233], v[100:103]
	v_mfma_f32_16x16x32_bf16 v[60:63], v[150:153], v[230:233], v[60:63]
	v_mfma_f32_16x16x32_bf16 v[84:87], v[138:141], v[238:241], v[84:87]
	v_mfma_f32_16x16x32_bf16 v[52:55], v[150:153], v[238:241], v[52:55]
	s_setprio 0
	s_setprio 1
	v_mfma_f32_16x16x32_bf16 v[40:43], v[154:157], v[170:173], v[40:43]
	v_mfma_f32_16x16x32_bf16 v[12:15], v[162:165], v[170:173], v[12:15]
	v_mfma_f32_16x16x32_bf16 v[32:35], v[154:157], v[178:181], v[32:35]
	v_mfma_f32_16x16x32_bf16 v[8:11], v[162:165], v[178:181], v[8:11]
	v_mfma_f32_16x16x32_bf16 v[24:27], v[154:157], v[192:195], v[24:27]
	v_mfma_f32_16x16x32_bf16 v[4:7], v[162:165], v[192:195], v[4:7]
	v_mfma_f32_16x16x32_bf16 v[16:19], v[154:157], v[234:237], v[16:19]
	v_mfma_f32_16x16x32_bf16 v[0:3], v[162:165], v[234:237], v[0:3]
	v_mfma_f32_16x16x32_bf16 v[40:43], v[158:161], v[174:177], v[40:43]
	v_mfma_f32_16x16x32_bf16 v[12:15], v[166:169], v[174:177], v[12:15]
	v_mfma_f32_16x16x32_bf16 v[32:35], v[158:161], v[182:185], v[32:35]
	v_mfma_f32_16x16x32_bf16 v[8:11], v[166:169], v[182:185], v[8:11]
	v_mfma_f32_16x16x32_bf16 v[24:27], v[158:161], v[230:233], v[24:27]
	v_mfma_f32_16x16x32_bf16 v[4:7], v[166:169], v[230:233], v[4:7]
	v_mfma_f32_16x16x32_bf16 v[16:19], v[158:161], v[238:241], v[16:19]
	v_mfma_f32_16x16x32_bf16 v[0:3], v[166:169], v[238:241], v[0:3]
	s_setprio 0
	s_add_u32 s26, s26, 0x100
	s_addc_u32 s27, s27, 0
	s_add_u32 s72, s72, 0x100
	s_addc_u32 s73, s73, 0
	s_cmp_ge_u32 s74, s52
	s_mov_b32 s28, s74
	s_barrier
	s_cbranch_scc0 .LBB0_1642
	s_and_b64 vcc, exec, s[14:15]
	s_cbranch_vccz .LBB0_1645
	s_barrier

; #define PG8_STAGE(bufoff, gbase, voff) do { _Pragma("unroll") for (int _i = 0; _i < 2; ++_i) \
;         __builtin_amdgcn_global_load_lds((const unsigned*)((const char*)(gbase) + (voff)[_i]), (PG8_LAS unsigned*)(lds + (bufoff) + ldsw + _i * 8192), 16, 0, 0); } while (0)
; #define PG8_LDA(dst, b, h) do { _Pragma("unroll") for (int m = 0; m < 4; ++m) _Pragma("unroll") for (int k = 0; k < 2; ++k) dst[m][k] = *(const PG8_LAS bf16x8*)(lds + PG8_SA(b, h) + aoff + m * 2048 + k * 1024); } while (0)
; #define PG8_LDB(dst, b, h) do { _Pragma("unroll") for (int n = 0; n < 2; ++n) _Pragma("unroll") for (int k = 0; k < 2; ++k) dst[n][k] = *(const PG8_LAS bf16x8*)(lds + PG8_SB(b, h) + boff + n * 2048 + k * 1024); } while (0)
; #define PG8_MMA(ai, bj, At, Bt) do { __builtin_amdgcn_s_setprio(1); _Pragma("unroll") for (int m = 0; m < 4; ++m) _Pragma("unroll") for (int n = 0; n < 2; ++n) _Pragma("unroll") for (int k = 0; k < 2; ++k) \
;         acc[ai][bj][m][n] = __builtin_amdgcn_mfma_f32_16x16x32_bf16(Bt[n][k], At[m][k], acc[ai][bj][m][n], 0, 0, 0); __builtin_amdgcn_s_setprio(0); } while (0)
; #define PG8_WAIT_V(n) asm volatile("s_waitcnt vmcnt(" #n ")" ::: "memory")
; #define PG8_WAIT_L(n) asm volatile("s_waitcnt lgkmcnt(" #n ")" ::: "memory")
; #define PG8_BAR __builtin_amdgcn_s_barrier()
; #define PG8_SCHED __builtin_amdgcn_sched_barrier(0)
; template <class Epi, class Sched, bool ALIGN_EPI = false, bool SP2 = false>
; __device__ __forceinline__ void gemm_phase(PG8_LAS unsigned char* lds, const Gemm g, const Sched& S, const Epi& E) {
;     ...
;             PG8_LDB(B0, 0, 0); PG8_LDB(B1, 0, 1); PG8_SCHED; PG8_LDA(At, 0, 0); PG8_STAGE(PG8_SA(1, 1), a1 + hstepA, voffA);
;             PG8_WAIT_V(8); PG8_WAIT_L(0); PG8_BAR; PG8_MMA(0, 0, At, B0); PG8_MMA(0, 1, At, B1); PG8_BAR; PG8_SCHED;
;             PG8_LDA(At, 0, 1); PG8_STAGE(PG8_SB(0, 0), b2, voffB); PG8_STAGE(PG8_SB(0, 1), b2 + hstepB, voffB); PG8_STAGE(PG8_SA(0, 0), a2, voffA);
;             PG8_WAIT_V(8); PG8_WAIT_L(0); PG8_BAR; PG8_MMA(1, 0, At, B0); PG8_MMA(1, 1, At, B1); PG8_BAR; PG8_SCHED;
.LBB0_1800:
	v_add_u32_e32 v140, 0x10000, v229
	v_add_u32_e32 v156, 0x14000, v229
	ds_read_b128 v[128:131], v140
	ds_read_b128 v[132:135], v140 offset:1024
	ds_read_b128 v[136:139], v140 offset:2048
	ds_read_b128 v[140:143], v140 offset:3072
	ds_read_b128 v[144:147], v156
	ds_read_b128 v[148:151], v156 offset:1024
	ds_read_b128 v[152:155], v156 offset:2048
	ds_read_b128 v[156:159], v156 offset:3072
	ds_read_b128 v[160:163], v230
	ds_read_b128 v[164:167], v230 offset:1024
	ds_read_b128 v[178:181], v230 offset:2048
	ds_read_b128 v[182:185], v230 offset:3072
	ds_read_b128 v[192:195], v230 offset:4096
	ds_read_b128 v[232:235], v230 offset:5120
	ds_read_b128 v[236:239], v230 offset:6144
	ds_read_b128 v[240:243], v230 offset:7168
	s_add_u32 s10, s8, 0xfffc0080
	s_addc_u32 s11, s9, -1
	s_add_i32 s71, 0, 0x10000
	s_cmp_eq_u32 s70, 12
	s_cselect_b32 s45, s13, s11
	s_cselect_b32 s44, s15, s10
	s_cselect_b32 s11, s35, s47
	s_cselect_b32 s10, s37, s46
	s_add_i32 s74, 0, 0x14000
	s_add_i32 m0, s54, 0xc000
	v_lshl_add_u64 v[186:187], s[8:9], 0, v[174:175]
	global_load_lds_dwordx4 v[186:187], off
	s_add_i32 m0, s54, 0xe000
	v_lshl_add_u64 v[186:187], s[8:9], 0, v[176:177]
	global_load_lds_dwordx4 v[186:187], off
	s_waitcnt vmcnt(8)
	s_waitcnt lgkmcnt(0)
	s_barrier
	s_setprio 1
	s_waitcnt lgkmcnt(0)
	v_mfma_f32_16x16x32_bf16 v[124:127], v[128:131], v[160:163], v[124:127]
	v_mfma_f32_16x16x32_bf16 v[60:63], v[136:139], v[160:163], v[60:63]
	v_mfma_f32_16x16x32_bf16 v[120:123], v[128:131], v[178:181], v[120:123]
	v_mfma_f32_16x16x32_bf16 v[56:59], v[136:139], v[178:181], v[56:59]
	v_mfma_f32_16x16x32_bf16 v[108:111], v[128:131], v[192:195], v[108:111]
	v_mfma_f32_16x16x32_bf16 v[44:47], v[136:139], v[192:195], v[44:47]
	v_mfma_f32_16x16x32_bf16 v[100:103], v[128:131], v[236:239], v[100:103]
	v_mfma_f32_16x16x32_bf16 v[36:39], v[136:139], v[236:239], v[36:39]
	v_mfma_f32_16x16x32_bf16 v[124:127], v[132:135], v[164:167], v[124:127]
	v_mfma_f32_16x16x32_bf16 v[60:63], v[140:143], v[164:167], v[60:63]
	v_mfma_f32_16x16x32_bf16 v[120:123], v[132:135], v[182:185], v[120:123]
	v_mfma_f32_16x16x32_bf16 v[56:59], v[140:143], v[182:185], v[56:59]
	v_mfma_f32_16x16x32_bf16 v[108:111], v[132:135], v[232:235], v[108:111]
	v_mfma_f32_16x16x32_bf16 v[44:47], v[140:143], v[232:235], v[44:47]
	v_mfma_f32_16x16x32_bf16 v[100:103], v[132:135], v[240:243], v[100:103]
	v_mfma_f32_16x16x32_bf16 v[36:39], v[140:143], v[240:243], v[36:39]
	s_setprio 0
	s_setprio 1
	v_mfma_f32_16x16x32_bf16 v[116:119], v[144:147], v[160:163], v[116:119]
	v_mfma_f32_16x16x32_bf16 v[52:55], v[152:155], v[160:163], v[52:55]
	v_mfma_f32_16x16x32_bf16 v[112:115], v[144:147], v[178:181], v[112:115]
	v_mfma_f32_16x16x32_bf16 v[48:51], v[152:155], v[178:181], v[48:51]
	v_mfma_f32_16x16x32_bf16 v[104:107], v[144:147], v[192:195], v[104:107]
	v_mfma_f32_16x16x32_bf16 v[40:43], v[152:155], v[192:195], v[40:43]
	v_mfma_f32_16x16x32_bf16 v[96:99], v[144:147], v[236:239], v[96:99]
	v_mfma_f32_16x16x32_bf16 v[32:35], v[152:155], v[236:239], v[32:35]
	v_mfma_f32_16x16x32_bf16 v[116:119], v[148:151], v[164:167], v[116:119]
	v_mfma_f32_16x16x32_bf16 v[52:55], v[156:159], v[164:167], v[52:55]
	v_mfma_f32_16x16x32_bf16 v[112:115], v[148:151], v[182:185], v[112:115]
	v_mfma_f32_16x16x32_bf16 v[48:51], v[156:159], v[182:185], v[48:51]
	v_mfma_f32_16x16x32_bf16 v[104:107], v[148:151], v[232:235], v[104:107]
	v_mfma_f32_16x16x32_bf16 v[40:43], v[156:159], v[232:235], v[40:43]
	v_mfma_f32_16x16x32_bf16 v[96:99], v[148:151], v[240:243], v[96:99]
	v_mfma_f32_16x16x32_bf16 v[32:35], v[156:159], v[240:243], v[32:35]
	s_setprio 0
	s_barrier
	ds_read_b128 v[160:163], v230 offset:16384
	ds_read_b128 v[164:167], v230 offset:17408
	ds_read_b128 v[178:181], v230 offset:18432
	ds_read_b128 v[182:185], v230 offset:19456
	ds_read_b128 v[192:195], v230 offset:20480
	ds_read_b128 v[232:235], v230 offset:21504
	ds_read_b128 v[236:239], v230 offset:22528
	ds_read_b128 v[240:243], v230 offset:23552
	s_add_i32 s71, s71, s53
	s_mov_b32 m0, s71
	v_lshl_add_u64 v[186:187], s[10:11], 0, v[188:189]
	global_load_lds_dwordx4 v[186:187], off
	s_add_i32 m0, s71, 0x2000
	s_add_u32 s72, s10, 0x40000
	v_lshl_add_u64 v[244:245], s[10:11], 0, v[172:173]
	s_addc_u32 s73, s11, 0
	s_add_i32 s71, s74, s53
	global_load_lds_dwordx4 v[244:245], off
	v_lshl_add_u64 v[246:247], s[72:73], 0, v[188:189]
	s_mov_b32 m0, s71
	v_lshl_add_u64 v[248:249], s[44:45], 0, v[170:171]
	global_load_lds_dwordx4 v[246:247], off
	s_add_i32 m0, s71, 0x2000
	v_lshl_add_u64 v[246:247], s[72:73], 0, v[172:173]
	global_load_lds_dwordx4 v[246:247], off
	s_mov_b32 m0, s54
	v_lshl_add_u64 v[246:247], s[44:45], 0, v[168:169]
	global_load_lds_dwordx4 v[246:247], off
	s_mov_b32 m0, s55
	s_nop 0
	global_load_lds_dwordx4 v[248:249], off
	s_waitcnt vmcnt(8)
	s_waitcnt lgkmcnt(0)
	s_barrier
; #define PG8_STAGE(bufoff, gbase, voff) do { _Pragma("unroll") for (int _i = 0; _i < 2; ++_i) \
;         __builtin_amdgcn_global_load_lds((const unsigned*)((const char*)(gbase) + (voff)[_i]), (PG8_LAS unsigned*)(lds + (bufoff) + ldsw + _i * 8192), 16, 0, 0); } while (0)
; #define PG8_LDA(dst, b, h) do { _Pragma("unroll") for (int m = 0; m < 4; ++m) _Pragma("unroll") for (int k = 0; k < 2; ++k) dst[m][k] = *(const PG8_LAS bf16x8*)(lds + PG8_SA(b, h) + aoff + m * 2048 + k * 1024); } while (0)
; #define PG8_LDB(dst, b, h) do { _Pragma("unroll") for (int n = 0; n < 2; ++n) _Pragma("unroll") for (int k = 0; k < 2; ++k) dst[n][k] = *(const PG8_LAS bf16x8*)(lds + PG8_SB(b, h) + boff + n * 2048 + k * 1024); } while (0)
; #define PG8_MMA(ai, bj, At, Bt) do { __builtin_amdgcn_s_setprio(1); _Pragma("unroll") for (int m = 0; m < 4; ++m) _Pragma("unroll") for (int n = 0; n < 2; ++n) _Pragma("unroll") for (int k = 0; k < 2; ++k) \
;         acc[ai][bj][m][n] = __builtin_amdgcn_mfma_f32_16x16x32_bf16(Bt[n][k], At[m][k], acc[ai][bj][m][n], 0, 0, 0); __builtin_amdgcn_s_setprio(0); } while (0)
; #define PG8_WAIT_V(n) asm volatile("s_waitcnt vmcnt(" #n ")" ::: "memory")
; #define PG8_WAIT_L(n) asm volatile("s_waitcnt lgkmcnt(" #n ")" ::: "memory")
; #define PG8_BAR __builtin_amdgcn_s_barrier()
; #define PG8_SCHED __builtin_amdgcn_sched_barrier(0)
; template <class Epi, class Sched, bool ALIGN_EPI = false, bool SP2 = false>
; __device__ __forceinline__ void gemm_phase(PG8_LAS unsigned char* lds, const Gemm g, const Sched& S, const Epi& E) {
;     ...
;             PG8_WAIT_V(8); PG8_WAIT_L(0); PG8_BAR; PG8_MMA(1, 0, At, B0); PG8_MMA(1, 1, At, B1); PG8_BAR; PG8_SCHED;
;             PG8_LDB(B0, 1, 0); PG8_LDB(B1, 1, 1); PG8_SCHED; PG8_LDA(At, 1, 0); PG8_STAGE(PG8_SA(0, 1), a2 + hstepA, voffA);
;             PG8_WAIT_V(8); PG8_WAIT_L(0); PG8_BAR; PG8_MMA(0, 0, At, B0); PG8_MMA(0, 1, At, B1); PG8_BAR; PG8_SCHED;
	s_setprio 1
	s_waitcnt lgkmcnt(0)
	v_mfma_f32_16x16x32_bf16 v[92:95], v[128:131], v[160:163], v[92:95]
	v_mfma_f32_16x16x32_bf16 v[28:31], v[136:139], v[160:163], v[28:31]
	v_mfma_f32_16x16x32_bf16 v[88:91], v[128:131], v[178:181], v[88:91]
	v_mfma_f32_16x16x32_bf16 v[24:27], v[136:139], v[178:181], v[24:27]
	v_mfma_f32_16x16x32_bf16 v[76:79], v[128:131], v[192:195], v[76:79]
	v_mfma_f32_16x16x32_bf16 v[12:15], v[136:139], v[192:195], v[12:15]
	v_mfma_f32_16x16x32_bf16 v[68:71], v[128:131], v[236:239], v[68:71]
	v_mfma_f32_16x16x32_bf16 v[4:7], v[136:139], v[236:239], v[4:7]
	v_mfma_f32_16x16x32_bf16 v[92:95], v[132:135], v[164:167], v[92:95]
	v_mfma_f32_16x16x32_bf16 v[28:31], v[140:143], v[164:167], v[28:31]
	v_mfma_f32_16x16x32_bf16 v[88:91], v[132:135], v[182:185], v[88:91]
	v_mfma_f32_16x16x32_bf16 v[24:27], v[140:143], v[182:185], v[24:27]
	v_mfma_f32_16x16x32_bf16 v[76:79], v[132:135], v[232:235], v[76:79]
	v_mfma_f32_16x16x32_bf16 v[12:15], v[140:143], v[232:235], v[12:15]
	v_mfma_f32_16x16x32_bf16 v[68:71], v[132:135], v[240:243], v[68:71]
	v_mfma_f32_16x16x32_bf16 v[4:7], v[140:143], v[240:243], v[4:7]
	s_setprio 0
	s_setprio 1
	v_mfma_f32_16x16x32_bf16 v[84:87], v[144:147], v[160:163], v[84:87]
	v_mfma_f32_16x16x32_bf16 v[20:23], v[152:155], v[160:163], v[20:23]
	v_mfma_f32_16x16x32_bf16 v[80:83], v[144:147], v[178:181], v[80:83]
	v_mfma_f32_16x16x32_bf16 v[16:19], v[152:155], v[178:181], v[16:19]
	v_mfma_f32_16x16x32_bf16 v[72:75], v[144:147], v[192:195], v[72:75]
	v_mfma_f32_16x16x32_bf16 v[8:11], v[152:155], v[192:195], v[8:11]
	v_mfma_f32_16x16x32_bf16 v[64:67], v[144:147], v[236:239], v[64:67]
	v_mfma_f32_16x16x32_bf16 v[0:3], v[152:155], v[236:239], v[0:3]
	v_mfma_f32_16x16x32_bf16 v[84:87], v[148:151], v[164:167], v[84:87]
	v_mfma_f32_16x16x32_bf16 v[20:23], v[156:159], v[164:167], v[20:23]
	v_mfma_f32_16x16x32_bf16 v[80:83], v[148:151], v[182:185], v[80:83]
	v_mfma_f32_16x16x32_bf16 v[16:19], v[156:159], v[182:185], v[16:19]
	v_mfma_f32_16x16x32_bf16 v[72:75], v[148:151], v[232:235], v[72:75]
	v_mfma_f32_16x16x32_bf16 v[8:11], v[156:159], v[232:235], v[8:11]
	v_mfma_f32_16x16x32_bf16 v[64:67], v[148:151], v[240:243], v[64:67]
	v_mfma_f32_16x16x32_bf16 v[0:3], v[156:159], v[240:243], v[0:3]
	s_setprio 0
	s_barrier
	v_add_u32_e32 v140, 0x18000, v229
	v_add_u32_e32 v156, 0x1c000, v229
	ds_read_b128 v[128:131], v140
	ds_read_b128 v[132:135], v140 offset:1024
	ds_read_b128 v[136:139], v140 offset:2048
	ds_read_b128 v[140:143], v140 offset:3072
	ds_read_b128 v[144:147], v156
	ds_read_b128 v[148:151], v156 offset:1024
	ds_read_b128 v[152:155], v156 offset:2048
	ds_read_b128 v[156:159], v156 offset:3072
	ds_read_b128 v[160:163], v230 offset:32768
	ds_read_b128 v[164:167], v230 offset:33792
	ds_read_b128 v[178:181], v230 offset:34816
	ds_read_b128 v[182:185], v230 offset:35840
	ds_read_b128 v[192:195], v230 offset:36864
	ds_read_b128 v[232:235], v230 offset:37888
	ds_read_b128 v[236:239], v230 offset:38912
	ds_read_b128 v[240:243], v230 offset:39936
	s_add_i32 s71, 0, 0x18000
	s_add_i32 s72, 0, 0x1c000
	s_add_u32 s44, s44, 0x40000
	s_addc_u32 s45, s45, 0
	s_mov_b32 m0, s56
	v_lshl_add_u64 v[250:251], s[44:45], 0, v[168:169]
	global_load_lds_dwordx4 v[250:251], off
	s_mov_b32 m0, s57
	v_lshl_add_u64 v[250:251], s[44:45], 0, v[170:171]
	global_load_lds_dwordx4 v[250:251], off
	s_waitcnt vmcnt(8)
	s_waitcnt lgkmcnt(0)
	s_barrier
	s_setprio 1
	s_waitcnt lgkmcnt(0)
	v_mfma_f32_16x16x32_bf16 v[124:127], v[128:131], v[160:163], v[124:127]
	v_mfma_f32_16x16x32_bf16 v[60:63], v[136:139], v[160:163], v[60:63]
	v_mfma_f32_16x16x32_bf16 v[120:123], v[128:131], v[178:181], v[120:123]
	v_mfma_f32_16x16x32_bf16 v[56:59], v[136:139], v[178:181], v[56:59]
	v_mfma_f32_16x16x32_bf16 v[108:111], v[128:131], v[192:195], v[108:111]
	v_mfma_f32_16x16x32_bf16 v[44:47], v[136:139], v[192:195], v[44:47]
	v_mfma_f32_16x16x32_bf16 v[100:103], v[128:131], v[236:239], v[100:103]
	v_mfma_f32_16x16x32_bf16 v[36:39], v[136:139], v[236:239], v[36:39]
	v_mfma_f32_16x16x32_bf16 v[124:127], v[132:135], v[164:167], v[124:127]
	v_mfma_f32_16x16x32_bf16 v[60:63], v[140:143], v[164:167], v[60:63]
	v_mfma_f32_16x16x32_bf16 v[120:123], v[132:135], v[182:185], v[120:123]
	v_mfma_f32_16x16x32_bf16 v[56:59], v[140:143], v[182:185], v[56:59]
	v_mfma_f32_16x16x32_bf16 v[108:111], v[132:135], v[232:235], v[108:111]
	v_mfma_f32_16x16x32_bf16 v[44:47], v[140:143], v[232:235], v[44:47]
	v_mfma_f32_16x16x32_bf16 v[100:103], v[132:135], v[240:243], v[100:103]
	v_mfma_f32_16x16x32_bf16 v[36:39], v[140:143], v[240:243], v[36:39]
	s_setprio 0
	s_setprio 1
	v_mfma_f32_16x16x32_bf16 v[116:119], v[144:147], v[160:163], v[116:119]
	v_mfma_f32_16x16x32_bf16 v[52:55], v[152:155], v[160:163], v[52:55]
	v_mfma_f32_16x16x32_bf16 v[112:115], v[144:147], v[178:181], v[112:115]
	v_mfma_f32_16x16x32_bf16 v[48:51], v[152:155], v[178:181], v[48:51]
	v_mfma_f32_16x16x32_bf16 v[104:107], v[144:147], v[192:195], v[104:107]
	v_mfma_f32_16x16x32_bf16 v[40:43], v[152:155], v[192:195], v[40:43]
	v_mfma_f32_16x16x32_bf16 v[96:99], v[144:147], v[236:239], v[96:99]
	v_mfma_f32_16x16x32_bf16 v[32:35], v[152:155], v[236:239], v[32:35]
	v_mfma_f32_16x16x32_bf16 v[116:119], v[148:151], v[164:167], v[116:119]
	v_mfma_f32_16x16x32_bf16 v[52:55], v[156:159], v[164:167], v[52:55]
	v_mfma_f32_16x16x32_bf16 v[112:115], v[148:151], v[182:185], v[112:115]
	v_mfma_f32_16x16x32_bf16 v[48:51], v[156:159], v[182:185], v[48:51]
	v_mfma_f32_16x16x32_bf16 v[104:107], v[148:151], v[232:235], v[104:107]
	v_mfma_f32_16x16x32_bf16 v[40:43], v[156:159], v[232:235], v[40:43]
	v_mfma_f32_16x16x32_bf16 v[96:99], v[148:151], v[240:243], v[96:99]
	v_mfma_f32_16x16x32_bf16 v[32:35], v[156:159], v[240:243], v[32:35]
	s_setprio 0
	s_barrier
; #define PG8_STAGE(bufoff, gbase, voff) do { _Pragma("unroll") for (int _i = 0; _i < 2; ++_i) \
;         __builtin_amdgcn_global_load_lds((const unsigned*)((const char*)(gbase) + (voff)[_i]), (PG8_LAS unsigned*)(lds + (bufoff) + ldsw + _i * 8192), 16, 0, 0); } while (0)
; #define PG8_LDA(dst, b, h) do { _Pragma("unroll") for (int m = 0; m < 4; ++m) _Pragma("unroll") for (int k = 0; k < 2; ++k) dst[m][k] = *(const PG8_LAS bf16x8*)(lds + PG8_SA(b, h) + aoff + m * 2048 + k * 1024); } while (0)
; #define PG8_WAIT_V(n) asm volatile("s_waitcnt vmcnt(" #n ")" ::: "memory")
; template <class Epi, class Sched, bool ALIGN_EPI = false, bool SP2 = false>
; __device__ __forceinline__ void gemm_phase(PG8_LAS unsigned char* lds, const Gemm g, const Sched& S, const Epi& E) {
;     ...
;             PG8_LDA(At, 1, 1); PG8_STAGE(PG8_SB(1, 0), b3, voffB); PG8_STAGE(PG8_SB(1, 1), b3 + hstepB, voffB); PG8_STAGE(PG8_SA(1, 0), a3, voffA);
;             PG8_WAIT_V(8); PG8_WAIT_L(0); PG8_BAR; PG8_MMA(1, 0, At, B0); PG8_MMA(1, 1, At, B1); PG8_BAR; PG8_SCHED;
;             } else {
;             PG8_LDB(B0, 0, 0); PG8_SCHED; PG8_LDA(At, 0, 0); PG8_STAGE(PG8_SA(1, 1), a1 + hstepA, voffA);
;             PG8_WAIT_L(8); PG8_BAR; PG8_WAIT_L(0); PG8_MMA(0, 0, At, B0); PG8_BAR; PG8_SCHED;
;             PG8_LDB(B1, 0, 1); PG8_STAGE(PG8_SB(0, 0), b2, voffB);
;             PG8_BAR; PG8_WAIT_L(0); PG8_MMA(0, 1, At, B1); PG8_BAR;
;             PG8_LDA(At, 0, 1); PG8_STAGE(PG8_SA(0, 0), a2, voffA);
;             PG8_BAR; PG8_WAIT_L(0); PG8_MMA(1, 0, At, B0); PG8_BAR; PG8_SCHED;
;             PG8_STAGE(PG8_SB(0, 1), b2 + hstepB, voffB);
;             PG8_WAIT_V(6); PG8_BAR; PG8_MMA(1, 1, At, B1); PG8_BAR;
;             PG8_LDB(B0, 1, 0); PG8_SCHED; PG8_LDA(At, 1, 0); PG8_STAGE(PG8_SA(0, 1), a2 + hstepA, voffA);
;             PG8_WAIT_L(8); PG8_BAR; PG8_WAIT_L(0); PG8_MMA(0, 0, At, B0); PG8_BAR; PG8_SCHED;
;             PG8_LDB(B1, 1, 1); PG8_STAGE(PG8_SB(1, 0), b3, voffB);
;             PG8_BAR; PG8_WAIT_L(0); PG8_MMA(0, 1, At, B1); PG8_BAR;
;             PG8_LDA(At, 1, 1); PG8_STAGE(PG8_SA(1, 0), a3, voffA);
;             PG8_BAR; PG8_WAIT_L(0); PG8_MMA(1, 0, At, B0); PG8_BAR; PG8_SCHED;
;             PG8_STAGE(PG8_SB(1, 1), b3 + hstepB, voffB);
;             PG8_WAIT_V(6); PG8_BAR; PG8_MMA(1, 1, At, B1); PG8_BAR;
;             }
;         }
;         if constexpr (ALIGN_EPI) { if (wr == 0) PG8_BAR; }
	ds_read_b128 v[160:163], v230 offset:49152
	ds_read_b128 v[164:167], v230 offset:50176
	ds_read_b128 v[178:181], v230 offset:51200
	ds_read_b128 v[182:185], v230 offset:52224
	ds_read_b128 v[192:195], v230 offset:53248
	ds_read_b128 v[232:235], v230 offset:54272
	ds_read_b128 v[236:239], v230 offset:55296
	ds_read_b128 v[240:243], v230 offset:56320
	s_add_i32 s44, s71, s53
	s_mov_b32 m0, s44
	v_lshl_add_u64 v[186:187], v[186:187], 0, s[94:95]
	global_load_lds_dwordx4 v[186:187], off
	s_add_i32 m0, s44, 0x2000
	s_add_u32 s10, s10, 0x40080
	v_lshl_add_u64 v[186:187], v[244:245], 0, s[94:95]
	s_addc_u32 s11, s11, 0
	s_add_i32 s44, s72, s53
	global_load_lds_dwordx4 v[186:187], off
	s_mov_b32 m0, s44
	v_lshl_add_u64 v[186:187], s[10:11], 0, v[188:189]
	global_load_lds_dwordx4 v[186:187], off
	s_add_i32 m0, s44, 0x2000
	v_lshl_add_u64 v[186:187], s[10:11], 0, v[172:173]
	global_load_lds_dwordx4 v[186:187], off
	s_mov_b32 m0, s60
	v_lshl_add_u64 v[186:187], v[246:247], 0, s[94:95]
	global_load_lds_dwordx4 v[186:187], off
	s_mov_b32 m0, s61
	v_lshl_add_u64 v[186:187], v[248:249], 0, s[94:95]
	global_load_lds_dwordx4 v[186:187], off
	s_waitcnt vmcnt(8)
	s_waitcnt lgkmcnt(0)
	s_barrier
	s_setprio 1
	s_waitcnt lgkmcnt(0)
	v_mfma_f32_16x16x32_bf16 v[92:95], v[128:131], v[160:163], v[92:95]
	v_mfma_f32_16x16x32_bf16 v[28:31], v[136:139], v[160:163], v[28:31]
	v_mfma_f32_16x16x32_bf16 v[88:91], v[128:131], v[178:181], v[88:91]
	v_mfma_f32_16x16x32_bf16 v[24:27], v[136:139], v[178:181], v[24:27]
	v_mfma_f32_16x16x32_bf16 v[76:79], v[128:131], v[192:195], v[76:79]
	v_mfma_f32_16x16x32_bf16 v[12:15], v[136:139], v[192:195], v[12:15]
	v_mfma_f32_16x16x32_bf16 v[68:71], v[128:131], v[236:239], v[68:71]
	v_mfma_f32_16x16x32_bf16 v[4:7], v[136:139], v[236:239], v[4:7]
	v_mfma_f32_16x16x32_bf16 v[92:95], v[132:135], v[164:167], v[92:95]
	v_mfma_f32_16x16x32_bf16 v[28:31], v[140:143], v[164:167], v[28:31]
	v_mfma_f32_16x16x32_bf16 v[88:91], v[132:135], v[182:185], v[88:91]
	v_mfma_f32_16x16x32_bf16 v[24:27], v[140:143], v[182:185], v[24:27]
	v_mfma_f32_16x16x32_bf16 v[76:79], v[132:135], v[232:235], v[76:79]
	v_mfma_f32_16x16x32_bf16 v[12:15], v[140:143], v[232:235], v[12:15]
	v_mfma_f32_16x16x32_bf16 v[68:71], v[132:135], v[240:243], v[68:71]
	v_mfma_f32_16x16x32_bf16 v[4:7], v[140:143], v[240:243], v[4:7]
	s_setprio 0
	s_setprio 1
	v_mfma_f32_16x16x32_bf16 v[84:87], v[144:147], v[160:163], v[84:87]
	v_mfma_f32_16x16x32_bf16 v[20:23], v[152:155], v[160:163], v[20:23]
	v_mfma_f32_16x16x32_bf16 v[80:83], v[144:147], v[178:181], v[80:83]
	v_mfma_f32_16x16x32_bf16 v[16:19], v[152:155], v[178:181], v[16:19]
	v_mfma_f32_16x16x32_bf16 v[72:75], v[144:147], v[192:195], v[72:75]
	v_mfma_f32_16x16x32_bf16 v[8:11], v[152:155], v[192:195], v[8:11]
	v_mfma_f32_16x16x32_bf16 v[64:67], v[144:147], v[236:239], v[64:67]
	v_mfma_f32_16x16x32_bf16 v[0:3], v[152:155], v[236:239], v[0:3]
	v_mfma_f32_16x16x32_bf16 v[84:87], v[148:151], v[164:167], v[84:87]
	v_mfma_f32_16x16x32_bf16 v[20:23], v[156:159], v[164:167], v[20:23]
	v_mfma_f32_16x16x32_bf16 v[80:83], v[148:151], v[182:185], v[80:83]
	v_mfma_f32_16x16x32_bf16 v[16:19], v[156:159], v[182:185], v[16:19]
	v_mfma_f32_16x16x32_bf16 v[72:75], v[148:151], v[232:235], v[72:75]
	v_mfma_f32_16x16x32_bf16 v[8:11], v[156:159], v[232:235], v[8:11]
	v_mfma_f32_16x16x32_bf16 v[64:67], v[148:151], v[240:243], v[64:67]
	v_mfma_f32_16x16x32_bf16 v[0:3], v[156:159], v[240:243], v[0:3]
	s_setprio 0
	s_add_i32 s70, s70, 2
	s_add_u32 s8, s8, 0x100
	s_addc_u32 s9, s9, 0
	s_add_u32 s46, s46, 0x100
	s_addc_u32 s47, s47, 0
	s_cmp_gt_u32 s70, 13
	s_barrier
	s_cbranch_scc0 .LBB0_1800
	s_and_b64 vcc, exec, s[26:27]
	s_cbranch_vccz .LBB0_1803
	s_barrier

; #define PG8_STAGE(bufoff, gbase, voff) do { _Pragma("unroll") for (int _i = 0; _i < 2; ++_i) \
;         __builtin_amdgcn_global_load_lds((const unsigned*)((const char*)(gbase) + (voff)[_i]), (PG8_LAS unsigned*)(lds + (bufoff) + ldsw + _i * 8192), 16, 0, 0); } while (0)
; #define PG8_LDA(dst, b, h) do { _Pragma("unroll") for (int m = 0; m < 4; ++m) _Pragma("unroll") for (int k = 0; k < 2; ++k) dst[m][k] = *(const PG8_LAS bf16x8*)(lds + PG8_SA(b, h) + aoff + m * 2048 + k * 1024); } while (0)
; #define PG8_LDB(dst, b, h) do { _Pragma("unroll") for (int n = 0; n < 2; ++n) _Pragma("unroll") for (int k = 0; k < 2; ++k) dst[n][k] = *(const PG8_LAS bf16x8*)(lds + PG8_SB(b, h) + boff + n * 2048 + k * 1024); } while (0)
; #define PG8_MMA(ai, bj, At, Bt) do { __builtin_amdgcn_s_setprio(1); _Pragma("unroll") for (int m = 0; m < 4; ++m) _Pragma("unroll") for (int n = 0; n < 2; ++n) _Pragma("unroll") for (int k = 0; k < 2; ++k) \
;         acc[ai][bj][m][n] = __builtin_amdgcn_mfma_f32_16x16x32_bf16(Bt[n][k], At[m][k], acc[ai][bj][m][n], 0, 0, 0); __builtin_amdgcn_s_setprio(0); } while (0)
; #define PG8_WAIT_V(n) asm volatile("s_waitcnt vmcnt(" #n ")" ::: "memory")
; #define PG8_WAIT_L(n) asm volatile("s_waitcnt lgkmcnt(" #n ")" ::: "memory")
; #define PG8_BAR __builtin_amdgcn_s_barrier()
; #define PG8_SCHED __builtin_amdgcn_sched_barrier(0)
; template <class Epi, class Sched, bool ALIGN_EPI = false, bool SP2 = false>
; __device__ __forceinline__ void gemm_phase(PG8_LAS unsigned char* lds, const Gemm g, const Sched& S, const Epi& E) {
;     ...
;             PG8_LDB(B0, 0, 0); PG8_LDB(B1, 0, 1); PG8_SCHED; PG8_LDA(At, 0, 0); PG8_STAGE(PG8_SA(1, 1), a1 + hstepA, voffA);
;             PG8_WAIT_V(8); PG8_WAIT_L(0); PG8_BAR; PG8_MMA(0, 0, At, B0); PG8_MMA(0, 1, At, B1); PG8_BAR; PG8_SCHED;
;             PG8_LDA(At, 0, 1); PG8_STAGE(PG8_SB(0, 0), b2, voffB); PG8_STAGE(PG8_SB(0, 1), b2 + hstepB, voffB); PG8_STAGE(PG8_SA(0, 0), a2, voffA);
;             PG8_WAIT_V(8); PG8_WAIT_L(0); PG8_BAR; PG8_MMA(1, 0, At, B0); PG8_MMA(1, 1, At, B1); PG8_BAR; PG8_SCHED;
.LBB0_1993:
	v_add_u32_e32 v150, 0x10000, v140
	v_add_u32_e32 v166, 0x14000, v140
	ds_read_b128 v[134:137], v150
	ds_read_b128 v[142:145], v150 offset:1024
	ds_read_b128 v[146:149], v150 offset:2048
	ds_read_b128 v[150:153], v150 offset:3072
	ds_read_b128 v[154:157], v166
	ds_read_b128 v[158:161], v166 offset:1024
	ds_read_b128 v[162:165], v166 offset:2048
	ds_read_b128 v[166:169], v166 offset:3072
	ds_read_b128 v[170:173], v141
	ds_read_b128 v[174:177], v141 offset:1024
	ds_read_b128 v[178:181], v141 offset:2048
	ds_read_b128 v[182:185], v141 offset:3072
	ds_read_b128 v[192:195], v141 offset:4096
	ds_read_b128 v[230:233], v141 offset:5120
	ds_read_b128 v[234:237], v141 offset:6144
	ds_read_b128 v[238:241], v141 offset:7168
	s_add_u32 s24, s22, 0x100
	s_addc_u32 s25, s23, 0
	s_add_i32 s68, 0, 0x10000
	s_cmp_eq_u32 s67, 40
	s_cselect_b32 s29, s9, s25
	s_cselect_b32 s28, s8, s24
	s_cselect_b32 s27, s21, s66
	s_cselect_b32 s26, s20, s65
	s_add_i32 s69, 0, 0x14000
	s_add_i32 m0, s36, 0xc000
	v_lshl_add_u64 v[186:187], s[22:23], 0, v[130:131]
	global_load_lds_dwordx4 v[186:187], off
	s_add_i32 m0, s36, 0xe000
	v_lshl_add_u64 v[186:187], s[22:23], 0, v[132:133]
	global_load_lds_dwordx4 v[186:187], off
	s_waitcnt vmcnt(8)
	s_waitcnt lgkmcnt(0)
	s_barrier
	s_setprio 1
	s_waitcnt lgkmcnt(0)
	v_mfma_f32_16x16x32_bf16 v[124:127], v[134:137], v[170:173], v[124:127]
	v_mfma_f32_16x16x32_bf16 v[96:99], v[146:149], v[170:173], v[96:99]
	v_mfma_f32_16x16x32_bf16 v[120:123], v[134:137], v[178:181], v[120:123]
	v_mfma_f32_16x16x32_bf16 v[92:95], v[146:149], v[178:181], v[92:95]
	v_mfma_f32_16x16x32_bf16 v[116:119], v[134:137], v[192:195], v[116:119]
	v_mfma_f32_16x16x32_bf16 v[84:87], v[146:149], v[192:195], v[84:87]
	v_mfma_f32_16x16x32_bf16 v[112:115], v[134:137], v[234:237], v[112:115]
	v_mfma_f32_16x16x32_bf16 v[80:83], v[146:149], v[234:237], v[80:83]
	v_mfma_f32_16x16x32_bf16 v[124:127], v[142:145], v[174:177], v[124:127]
	v_mfma_f32_16x16x32_bf16 v[96:99], v[150:153], v[174:177], v[96:99]
	v_mfma_f32_16x16x32_bf16 v[120:123], v[142:145], v[182:185], v[120:123]
	v_mfma_f32_16x16x32_bf16 v[92:95], v[150:153], v[182:185], v[92:95]
	v_mfma_f32_16x16x32_bf16 v[116:119], v[142:145], v[230:233], v[116:119]
	v_mfma_f32_16x16x32_bf16 v[84:87], v[150:153], v[230:233], v[84:87]
	v_mfma_f32_16x16x32_bf16 v[112:115], v[142:145], v[238:241], v[112:115]
	v_mfma_f32_16x16x32_bf16 v[80:83], v[150:153], v[238:241], v[80:83]
	s_setprio 0
	s_setprio 1
	v_mfma_f32_16x16x32_bf16 v[64:67], v[154:157], v[170:173], v[64:67]
	v_mfma_f32_16x16x32_bf16 v[36:39], v[162:165], v[170:173], v[36:39]
	v_mfma_f32_16x16x32_bf16 v[56:59], v[154:157], v[178:181], v[56:59]
	v_mfma_f32_16x16x32_bf16 v[24:27], v[162:165], v[178:181], v[24:27]
	v_mfma_f32_16x16x32_bf16 v[52:55], v[154:157], v[192:195], v[52:55]
	v_mfma_f32_16x16x32_bf16 v[20:23], v[162:165], v[192:195], v[20:23]
	v_mfma_f32_16x16x32_bf16 v[48:51], v[154:157], v[234:237], v[48:51]
	v_mfma_f32_16x16x32_bf16 v[16:19], v[162:165], v[234:237], v[16:19]
	v_mfma_f32_16x16x32_bf16 v[64:67], v[158:161], v[174:177], v[64:67]
	v_mfma_f32_16x16x32_bf16 v[36:39], v[166:169], v[174:177], v[36:39]
	v_mfma_f32_16x16x32_bf16 v[56:59], v[158:161], v[182:185], v[56:59]
	v_mfma_f32_16x16x32_bf16 v[24:27], v[166:169], v[182:185], v[24:27]
	v_mfma_f32_16x16x32_bf16 v[52:55], v[158:161], v[230:233], v[52:55]
	v_mfma_f32_16x16x32_bf16 v[20:23], v[166:169], v[230:233], v[20:23]
	v_mfma_f32_16x16x32_bf16 v[48:51], v[158:161], v[238:241], v[48:51]
	v_mfma_f32_16x16x32_bf16 v[16:19], v[166:169], v[238:241], v[16:19]
	s_setprio 0
	s_barrier
	ds_read_b128 v[170:173], v141 offset:16384
	ds_read_b128 v[174:177], v141 offset:17408
	ds_read_b128 v[178:181], v141 offset:18432
	ds_read_b128 v[182:185], v141 offset:19456
	ds_read_b128 v[192:195], v141 offset:20480
	ds_read_b128 v[230:233], v141 offset:21504
	ds_read_b128 v[234:237], v141 offset:22528
	ds_read_b128 v[238:241], v141 offset:23552
	s_add_i32 s22, s68, s35
	s_mov_b32 m0, s22
	v_lshl_add_u64 v[186:187], s[26:27], 0, v[188:189]
	global_load_lds_dwordx4 v[186:187], off
	s_add_i32 m0, s22, 0x2000
	s_add_u32 s22, s26, 0xb0000
	v_lshl_add_u64 v[196:197], s[26:27], 0, v[128:129]
	s_addc_u32 s23, s27, 0
	s_add_i32 s68, s69, s35
	global_load_lds_dwordx4 v[196:197], off
	v_lshl_add_u64 v[242:243], s[22:23], 0, v[188:189]
	s_mov_b32 m0, s68
	v_lshl_add_u64 v[244:245], s[28:29], 0, v[128:129]
	global_load_lds_dwordx4 v[242:243], off
	s_add_i32 m0, s68, 0x2000
	v_lshl_add_u64 v[242:243], s[22:23], 0, v[128:129]
	global_load_lds_dwordx4 v[242:243], off
	s_mov_b32 m0, s36
	v_lshl_add_u64 v[242:243], s[28:29], 0, v[188:189]
	global_load_lds_dwordx4 v[242:243], off
	s_mov_b32 m0, s37
	s_nop 0
	global_load_lds_dwordx4 v[244:245], off
	s_waitcnt vmcnt(8)
	s_waitcnt lgkmcnt(0)
	s_barrier
; #define PG8_STAGE(bufoff, gbase, voff) do { _Pragma("unroll") for (int _i = 0; _i < 2; ++_i) \
;         __builtin_amdgcn_global_load_lds((const unsigned*)((const char*)(gbase) + (voff)[_i]), (PG8_LAS unsigned*)(lds + (bufoff) + ldsw + _i * 8192), 16, 0, 0); } while (0)
; #define PG8_LDA(dst, b, h) do { _Pragma("unroll") for (int m = 0; m < 4; ++m) _Pragma("unroll") for (int k = 0; k < 2; ++k) dst[m][k] = *(const PG8_LAS bf16x8*)(lds + PG8_SA(b, h) + aoff + m * 2048 + k * 1024); } while (0)
; #define PG8_LDB(dst, b, h) do { _Pragma("unroll") for (int n = 0; n < 2; ++n) _Pragma("unroll") for (int k = 0; k < 2; ++k) dst[n][k] = *(const PG8_LAS bf16x8*)(lds + PG8_SB(b, h) + boff + n * 2048 + k * 1024); } while (0)
; #define PG8_MMA(ai, bj, At, Bt) do { __builtin_amdgcn_s_setprio(1); _Pragma("unroll") for (int m = 0; m < 4; ++m) _Pragma("unroll") for (int n = 0; n < 2; ++n) _Pragma("unroll") for (int k = 0; k < 2; ++k) \
;         acc[ai][bj][m][n] = __builtin_amdgcn_mfma_f32_16x16x32_bf16(Bt[n][k], At[m][k], acc[ai][bj][m][n], 0, 0, 0); __builtin_amdgcn_s_setprio(0); } while (0)
; #define PG8_WAIT_V(n) asm volatile("s_waitcnt vmcnt(" #n ")" ::: "memory")
; #define PG8_WAIT_L(n) asm volatile("s_waitcnt lgkmcnt(" #n ")" ::: "memory")
; #define PG8_BAR __builtin_amdgcn_s_barrier()
; #define PG8_SCHED __builtin_amdgcn_sched_barrier(0)
; template <class Epi, class Sched, bool ALIGN_EPI = false, bool SP2 = false>
; __device__ __forceinline__ void gemm_phase(PG8_LAS unsigned char* lds, const Gemm g, const Sched& S, const Epi& E) {
;     ...
;             PG8_WAIT_V(8); PG8_WAIT_L(0); PG8_BAR; PG8_MMA(1, 0, At, B0); PG8_MMA(1, 1, At, B1); PG8_BAR; PG8_SCHED;
;             PG8_LDB(B0, 1, 0); PG8_LDB(B1, 1, 1); PG8_SCHED; PG8_LDA(At, 1, 0); PG8_STAGE(PG8_SA(0, 1), a2 + hstepA, voffA);
;             PG8_WAIT_V(8); PG8_WAIT_L(0); PG8_BAR; PG8_MMA(0, 0, At, B0); PG8_MMA(0, 1, At, B1); PG8_BAR; PG8_SCHED;
	s_setprio 1
	s_waitcnt lgkmcnt(0)
	v_mfma_f32_16x16x32_bf16 v[108:111], v[134:137], v[170:173], v[108:111]
	v_mfma_f32_16x16x32_bf16 v[76:79], v[146:149], v[170:173], v[76:79]
	v_mfma_f32_16x16x32_bf16 v[104:107], v[134:137], v[178:181], v[104:107]
	v_mfma_f32_16x16x32_bf16 v[72:75], v[146:149], v[178:181], v[72:75]
	v_mfma_f32_16x16x32_bf16 v[100:103], v[134:137], v[192:195], v[100:103]
	v_mfma_f32_16x16x32_bf16 v[68:71], v[146:149], v[192:195], v[68:71]
	v_mfma_f32_16x16x32_bf16 v[88:91], v[134:137], v[234:237], v[88:91]
	v_mfma_f32_16x16x32_bf16 v[60:63], v[146:149], v[234:237], v[60:63]
	v_mfma_f32_16x16x32_bf16 v[108:111], v[142:145], v[174:177], v[108:111]
	v_mfma_f32_16x16x32_bf16 v[76:79], v[150:153], v[174:177], v[76:79]
	v_mfma_f32_16x16x32_bf16 v[104:107], v[142:145], v[182:185], v[104:107]
	v_mfma_f32_16x16x32_bf16 v[72:75], v[150:153], v[182:185], v[72:75]
	v_mfma_f32_16x16x32_bf16 v[100:103], v[142:145], v[230:233], v[100:103]
	v_mfma_f32_16x16x32_bf16 v[68:71], v[150:153], v[230:233], v[68:71]
	v_mfma_f32_16x16x32_bf16 v[88:91], v[142:145], v[238:241], v[88:91]
	v_mfma_f32_16x16x32_bf16 v[60:63], v[150:153], v[238:241], v[60:63]
	s_setprio 0
	s_setprio 1
	v_mfma_f32_16x16x32_bf16 v[44:47], v[154:157], v[170:173], v[44:47]
	v_mfma_f32_16x16x32_bf16 v[12:15], v[162:165], v[170:173], v[12:15]
	v_mfma_f32_16x16x32_bf16 v[40:43], v[154:157], v[178:181], v[40:43]
	v_mfma_f32_16x16x32_bf16 v[8:11], v[162:165], v[178:181], v[8:11]
	v_mfma_f32_16x16x32_bf16 v[32:35], v[154:157], v[192:195], v[32:35]
	v_mfma_f32_16x16x32_bf16 v[4:7], v[162:165], v[192:195], v[4:7]
	v_mfma_f32_16x16x32_bf16 v[28:31], v[154:157], v[234:237], v[28:31]
	v_mfma_f32_16x16x32_bf16 v[0:3], v[162:165], v[234:237], v[0:3]
	v_mfma_f32_16x16x32_bf16 v[44:47], v[158:161], v[174:177], v[44:47]
	v_mfma_f32_16x16x32_bf16 v[12:15], v[166:169], v[174:177], v[12:15]
	v_mfma_f32_16x16x32_bf16 v[40:43], v[158:161], v[182:185], v[40:43]
	v_mfma_f32_16x16x32_bf16 v[8:11], v[166:169], v[182:185], v[8:11]
	v_mfma_f32_16x16x32_bf16 v[32:35], v[158:161], v[230:233], v[32:35]
	v_mfma_f32_16x16x32_bf16 v[4:7], v[166:169], v[230:233], v[4:7]
	v_mfma_f32_16x16x32_bf16 v[28:31], v[158:161], v[238:241], v[28:31]
	v_mfma_f32_16x16x32_bf16 v[0:3], v[166:169], v[238:241], v[0:3]
	s_setprio 0
	s_barrier
	v_add_u32_e32 v150, 0x18000, v140
	v_add_u32_e32 v166, 0x1c000, v140
	ds_read_b128 v[134:137], v150
	ds_read_b128 v[142:145], v150 offset:1024
	ds_read_b128 v[146:149], v150 offset:2048
	ds_read_b128 v[150:153], v150 offset:3072
	ds_read_b128 v[154:157], v166
	ds_read_b128 v[158:161], v166 offset:1024
	ds_read_b128 v[162:165], v166 offset:2048
	ds_read_b128 v[166:169], v166 offset:3072
	ds_read_b128 v[170:173], v141 offset:32768
	ds_read_b128 v[174:177], v141 offset:33792
	ds_read_b128 v[178:181], v141 offset:34816
	ds_read_b128 v[182:185], v141 offset:35840
	ds_read_b128 v[192:195], v141 offset:36864
	ds_read_b128 v[230:233], v141 offset:37888
	ds_read_b128 v[234:237], v141 offset:38912
	ds_read_b128 v[238:241], v141 offset:39936
	s_add_i32 s68, 0, 0x18000
	s_add_i32 s69, 0, 0x1c000
	s_add_u32 s22, s28, 0xb0000
	s_addc_u32 s23, s29, 0
	s_mov_b32 m0, s44
	v_lshl_add_u64 v[246:247], s[22:23], 0, v[188:189]
	global_load_lds_dwordx4 v[246:247], off
	s_mov_b32 m0, s45
	v_lshl_add_u64 v[246:247], s[22:23], 0, v[128:129]
	global_load_lds_dwordx4 v[246:247], off
	s_waitcnt vmcnt(8)
	s_waitcnt lgkmcnt(0)
	s_barrier
	s_setprio 1
	s_waitcnt lgkmcnt(0)
	v_mfma_f32_16x16x32_bf16 v[124:127], v[134:137], v[170:173], v[124:127]
	v_mfma_f32_16x16x32_bf16 v[96:99], v[146:149], v[170:173], v[96:99]
	v_mfma_f32_16x16x32_bf16 v[120:123], v[134:137], v[178:181], v[120:123]
	v_mfma_f32_16x16x32_bf16 v[92:95], v[146:149], v[178:181], v[92:95]
	v_mfma_f32_16x16x32_bf16 v[116:119], v[134:137], v[192:195], v[116:119]
	v_mfma_f32_16x16x32_bf16 v[84:87], v[146:149], v[192:195], v[84:87]
	v_mfma_f32_16x16x32_bf16 v[112:115], v[134:137], v[234:237], v[112:115]
	v_mfma_f32_16x16x32_bf16 v[80:83], v[146:149], v[234:237], v[80:83]
	v_mfma_f32_16x16x32_bf16 v[124:127], v[142:145], v[174:177], v[124:127]
	v_mfma_f32_16x16x32_bf16 v[96:99], v[150:153], v[174:177], v[96:99]
	v_mfma_f32_16x16x32_bf16 v[120:123], v[142:145], v[182:185], v[120:123]
	v_mfma_f32_16x16x32_bf16 v[92:95], v[150:153], v[182:185], v[92:95]
	v_mfma_f32_16x16x32_bf16 v[116:119], v[142:145], v[230:233], v[116:119]
	v_mfma_f32_16x16x32_bf16 v[84:87], v[150:153], v[230:233], v[84:87]
	v_mfma_f32_16x16x32_bf16 v[112:115], v[142:145], v[238:241], v[112:115]
	v_mfma_f32_16x16x32_bf16 v[80:83], v[150:153], v[238:241], v[80:83]
	s_setprio 0
	s_setprio 1
	v_mfma_f32_16x16x32_bf16 v[64:67], v[154:157], v[170:173], v[64:67]
	v_mfma_f32_16x16x32_bf16 v[36:39], v[162:165], v[170:173], v[36:39]
	v_mfma_f32_16x16x32_bf16 v[56:59], v[154:157], v[178:181], v[56:59]
	v_mfma_f32_16x16x32_bf16 v[24:27], v[162:165], v[178:181], v[24:27]
	v_mfma_f32_16x16x32_bf16 v[52:55], v[154:157], v[192:195], v[52:55]
	v_mfma_f32_16x16x32_bf16 v[20:23], v[162:165], v[192:195], v[20:23]
	v_mfma_f32_16x16x32_bf16 v[48:51], v[154:157], v[234:237], v[48:51]
	v_mfma_f32_16x16x32_bf16 v[16:19], v[162:165], v[234:237], v[16:19]
	v_mfma_f32_16x16x32_bf16 v[64:67], v[158:161], v[174:177], v[64:67]
	v_mfma_f32_16x16x32_bf16 v[36:39], v[166:169], v[174:177], v[36:39]
	v_mfma_f32_16x16x32_bf16 v[56:59], v[158:161], v[182:185], v[56:59]
	v_mfma_f32_16x16x32_bf16 v[24:27], v[166:169], v[182:185], v[24:27]
	v_mfma_f32_16x16x32_bf16 v[52:55], v[158:161], v[230:233], v[52:55]
	v_mfma_f32_16x16x32_bf16 v[20:23], v[166:169], v[230:233], v[20:23]
	v_mfma_f32_16x16x32_bf16 v[48:51], v[158:161], v[238:241], v[48:51]
	v_mfma_f32_16x16x32_bf16 v[16:19], v[166:169], v[238:241], v[16:19]
	s_setprio 0
	s_barrier
; #define PG8_STAGE(bufoff, gbase, voff) do { _Pragma("unroll") for (int _i = 0; _i < 2; ++_i) \
;         __builtin_amdgcn_global_load_lds((const unsigned*)((const char*)(gbase) + (voff)[_i]), (PG8_LAS unsigned*)(lds + (bufoff) + ldsw + _i * 8192), 16, 0, 0); } while (0)
; #define PG8_LDA(dst, b, h) do { _Pragma("unroll") for (int m = 0; m < 4; ++m) _Pragma("unroll") for (int k = 0; k < 2; ++k) dst[m][k] = *(const PG8_LAS bf16x8*)(lds + PG8_SA(b, h) + aoff + m * 2048 + k * 1024); } while (0)
; #define PG8_WAIT_V(n) asm volatile("s_waitcnt vmcnt(" #n ")" ::: "memory")
; template <class Epi, class Sched, bool ALIGN_EPI = false, bool SP2 = false>
; __device__ __forceinline__ void gemm_phase(PG8_LAS unsigned char* lds, const Gemm g, const Sched& S, const Epi& E) {
;     ...
;             PG8_LDA(At, 1, 1); PG8_STAGE(PG8_SB(1, 0), b3, voffB); PG8_STAGE(PG8_SB(1, 1), b3 + hstepB, voffB); PG8_STAGE(PG8_SA(1, 0), a3, voffA);
;             PG8_WAIT_V(8); PG8_WAIT_L(0); PG8_BAR; PG8_MMA(1, 0, At, B0); PG8_MMA(1, 1, At, B1); PG8_BAR; PG8_SCHED;
;             } else {
;             PG8_LDB(B0, 0, 0); PG8_SCHED; PG8_LDA(At, 0, 0); PG8_STAGE(PG8_SA(1, 1), a1 + hstepA, voffA);
;             PG8_WAIT_L(8); PG8_BAR; PG8_WAIT_L(0); PG8_MMA(0, 0, At, B0); PG8_BAR; PG8_SCHED;
;             PG8_LDB(B1, 0, 1); PG8_STAGE(PG8_SB(0, 0), b2, voffB);
;             PG8_BAR; PG8_WAIT_L(0); PG8_MMA(0, 1, At, B1); PG8_BAR;
;             PG8_LDA(At, 0, 1); PG8_STAGE(PG8_SA(0, 0), a2, voffA);
;             PG8_BAR; PG8_WAIT_L(0); PG8_MMA(1, 0, At, B0); PG8_BAR; PG8_SCHED;
;             PG8_STAGE(PG8_SB(0, 1), b2 + hstepB, voffB);
;             PG8_WAIT_V(6); PG8_BAR; PG8_MMA(1, 1, At, B1); PG8_BAR;
;             PG8_LDB(B0, 1, 0); PG8_SCHED; PG8_LDA(At, 1, 0); PG8_STAGE(PG8_SA(0, 1), a2 + hstepA, voffA);
;             PG8_WAIT_L(8); PG8_BAR; PG8_WAIT_L(0); PG8_MMA(0, 0, At, B0); PG8_BAR; PG8_SCHED;
;             PG8_LDB(B1, 1, 1); PG8_STAGE(PG8_SB(1, 0), b3, voffB);
;             PG8_BAR; PG8_WAIT_L(0); PG8_MMA(0, 1, At, B1); PG8_BAR;
;             PG8_LDA(At, 1, 1); PG8_STAGE(PG8_SA(1, 0), a3, voffA);
;             PG8_BAR; PG8_WAIT_L(0); PG8_MMA(1, 0, At, B0); PG8_BAR; PG8_SCHED;
;             PG8_STAGE(PG8_SB(1, 1), b3 + hstepB, voffB);
;             PG8_WAIT_V(6); PG8_BAR; PG8_MMA(1, 1, At, B1); PG8_BAR;
;             }
;         }
;         if constexpr (ALIGN_EPI) { if (wr == 0) PG8_BAR; }
	ds_read_b128 v[170:173], v141 offset:49152
	ds_read_b128 v[174:177], v141 offset:50176
	ds_read_b128 v[178:181], v141 offset:51200
	ds_read_b128 v[182:185], v141 offset:52224
	ds_read_b128 v[192:195], v141 offset:53248
	ds_read_b128 v[230:233], v141 offset:54272
	ds_read_b128 v[234:237], v141 offset:55296
	ds_read_b128 v[238:241], v141 offset:56320
	s_add_i32 s22, s68, s35
	s_mov_b32 m0, s22
	v_lshl_add_u64 v[186:187], v[186:187], 0, s[94:95]
	global_load_lds_dwordx4 v[186:187], off
	s_add_i32 m0, s22, 0x2000
	s_add_u32 s22, s26, 0xb0080
	v_lshl_add_u64 v[186:187], v[196:197], 0, s[94:95]
	s_addc_u32 s23, s27, 0
	s_add_i32 s26, s69, s35
	global_load_lds_dwordx4 v[186:187], off
	s_mov_b32 m0, s26
	v_lshl_add_u64 v[186:187], s[22:23], 0, v[188:189]
	global_load_lds_dwordx4 v[186:187], off
	s_add_i32 m0, s26, 0x2000
	v_lshl_add_u64 v[186:187], s[22:23], 0, v[128:129]
	global_load_lds_dwordx4 v[186:187], off
	s_mov_b32 m0, s57
	v_lshl_add_u64 v[186:187], v[242:243], 0, s[94:95]
	global_load_lds_dwordx4 v[186:187], off
	s_mov_b32 m0, s58
	v_lshl_add_u64 v[186:187], v[244:245], 0, s[94:95]
	global_load_lds_dwordx4 v[186:187], off
	s_waitcnt vmcnt(8)
	s_waitcnt lgkmcnt(0)
	s_barrier
	s_setprio 1
	s_waitcnt lgkmcnt(0)
	v_mfma_f32_16x16x32_bf16 v[108:111], v[134:137], v[170:173], v[108:111]
	v_mfma_f32_16x16x32_bf16 v[76:79], v[146:149], v[170:173], v[76:79]
	v_mfma_f32_16x16x32_bf16 v[104:107], v[134:137], v[178:181], v[104:107]
	v_mfma_f32_16x16x32_bf16 v[72:75], v[146:149], v[178:181], v[72:75]
	v_mfma_f32_16x16x32_bf16 v[100:103], v[134:137], v[192:195], v[100:103]
	v_mfma_f32_16x16x32_bf16 v[68:71], v[146:149], v[192:195], v[68:71]
	v_mfma_f32_16x16x32_bf16 v[88:91], v[134:137], v[234:237], v[88:91]
	v_mfma_f32_16x16x32_bf16 v[60:63], v[146:149], v[234:237], v[60:63]
	v_mfma_f32_16x16x32_bf16 v[108:111], v[142:145], v[174:177], v[108:111]
	v_mfma_f32_16x16x32_bf16 v[76:79], v[150:153], v[174:177], v[76:79]
	v_mfma_f32_16x16x32_bf16 v[104:107], v[142:145], v[182:185], v[104:107]
	v_mfma_f32_16x16x32_bf16 v[72:75], v[150:153], v[182:185], v[72:75]
	v_mfma_f32_16x16x32_bf16 v[100:103], v[142:145], v[230:233], v[100:103]
	v_mfma_f32_16x16x32_bf16 v[68:71], v[150:153], v[230:233], v[68:71]
	v_mfma_f32_16x16x32_bf16 v[88:91], v[142:145], v[238:241], v[88:91]
	v_mfma_f32_16x16x32_bf16 v[60:63], v[150:153], v[238:241], v[60:63]
	s_setprio 0
	s_setprio 1
	v_mfma_f32_16x16x32_bf16 v[44:47], v[154:157], v[170:173], v[44:47]
	v_mfma_f32_16x16x32_bf16 v[12:15], v[162:165], v[170:173], v[12:15]
	v_mfma_f32_16x16x32_bf16 v[40:43], v[154:157], v[178:181], v[40:43]
	v_mfma_f32_16x16x32_bf16 v[8:11], v[162:165], v[178:181], v[8:11]
	v_mfma_f32_16x16x32_bf16 v[32:35], v[154:157], v[192:195], v[32:35]
	v_mfma_f32_16x16x32_bf16 v[4:7], v[162:165], v[192:195], v[4:7]
	v_mfma_f32_16x16x32_bf16 v[28:31], v[154:157], v[234:237], v[28:31]
	v_mfma_f32_16x16x32_bf16 v[0:3], v[162:165], v[234:237], v[0:3]
	v_mfma_f32_16x16x32_bf16 v[44:47], v[158:161], v[174:177], v[44:47]
	v_mfma_f32_16x16x32_bf16 v[12:15], v[166:169], v[174:177], v[12:15]
	v_mfma_f32_16x16x32_bf16 v[40:43], v[158:161], v[182:185], v[40:43]
	v_mfma_f32_16x16x32_bf16 v[8:11], v[166:169], v[182:185], v[8:11]
	v_mfma_f32_16x16x32_bf16 v[32:35], v[158:161], v[230:233], v[32:35]
	v_mfma_f32_16x16x32_bf16 v[4:7], v[166:169], v[230:233], v[4:7]
	v_mfma_f32_16x16x32_bf16 v[28:31], v[158:161], v[238:241], v[28:31]
	v_mfma_f32_16x16x32_bf16 v[0:3], v[166:169], v[238:241], v[0:3]
	s_setprio 0
	s_add_i32 s67, s67, 2
	s_add_u32 s65, s65, 0x100
	s_addc_u32 s66, s66, 0
	s_cmp_gt_u32 s67, 41
	s_mov_b64 s[22:23], s[24:25]
	s_barrier
	s_cbranch_scc0 .LBB0_1993
	s_and_b64 vcc, exec, s[14:15]
	s_cbranch_vccz .LBB0_1996
	s_barrier
